# nt cache policy on the weight-conversion stream loads and stores (RG-LRU background stream and the P0 transposes)
# speedup vs baseline: 1.0137x; 1.0013x over previous
; #define LAS __attribute__((address_space(3)))
; DI unsigned pk2(float lo, float hi) { f32x2 v = {lo, hi}; bf16v2 b = __builtin_convertvector(v, bf16v2); return __builtin_bit_cast(unsigned, b); }
; DI void p0_transpose_item(const float* W, int K, int N, bf16* WT, LAS uchar* scr, int item, int lane, const float* kscale = nullptr) {
;     const int nblk = N / 64, kb = item / nblk, nb = item % nblk, k0 = 64 * kb, n0 = 64 * nb;
;     const int q = lane >> 4, c16 = lane & 15;
;     f32x4 v[16];
; #pragma unroll
;     for (int i = 0; i < 16; ++i) v[i] = *(const f32x4*)(W + (size_t)(k0 + 16 * q + i) * N + n0 + 4 * c16);
;     if (kscale) {
; #pragma unroll
;         for (int i = 0; i < 16; ++i) v[i] = v[i] * kscale[k0 + 16 * q + i]; }
; #pragma unroll
;     for (int j = 0; j < 4; ++j) { u32x4 lo, hi;
;         lo.x = pk2(v[0][j], v[1][j]); lo.y = pk2(v[2][j], v[3][j]); lo.z = pk2(v[4][j], v[5][j]); lo.w = pk2(v[6][j], v[7][j]);
;         hi.x = pk2(v[8][j], v[9][j]); hi.y = pk2(v[10][j], v[11][j]); hi.z = pk2(v[12][j], v[13][j]); hi.w = pk2(v[14][j], v[15][j]);
;         LAS uchar* p = scr + (4 * c16 + j) * TSTR + q * 32; *(LAS u32x4*)p = lo; *(LAS u32x4*)(p + 16) = hi; }
;     asm volatile("s_waitcnt lgkmcnt(0)" ::: "memory");
;     const int c = lane & 7, nr = lane >> 3;
; #pragma unroll
;     for (int r = 0; r < 8; ++r) { const int n = nr + 8 * r;
;         *(u32x4*)(WT + (size_t)(n0 + n) * K + k0 + 8 * c) = *(const LAS u32x4*)(scr + n * TSTR + c * 16); }
;     asm volatile("s_waitcnt lgkmcnt(0)" ::: "memory");
; }
.LBB0_12:
	s_mul_hi_i32 s9, s8, 0x2aaaaaab
	s_lshr_b32 s10, s9, 31
	s_ashr_i32 s9, s9, 6
	s_add_i32 s9, s9, s10
	s_lshl_b32 s10, s9, 6
	s_mulk_i32 s9, 0xa000
	s_add_i32 s12, s3, s9
	v_or_b32_e32 v9, s10, v1
	s_ashr_i32 s13, s12, 31
	s_ashr_i32 s11, s10, 31
	v_or_b32_e32 v14, 1, v9
	v_or_b32_e32 v16, 2, v9
	v_or_b32_e32 v17, 3, v9
	v_or_b32_e32 v20, 4, v9
	v_or_b32_e32 v21, 5, v9
	v_or_b32_e32 v24, 6, v9
	v_or_b32_e32 v25, 7, v9
	v_or_b32_e32 v28, 8, v9
	v_or_b32_e32 v29, 9, v9
	v_or_b32_e32 v32, 10, v9
	v_or_b32_e32 v33, 11, v9
	v_or_b32_e32 v36, 12, v9
	v_or_b32_e32 v37, 13, v9
	v_or_b32_e32 v40, 14, v9
	v_or_b32_e32 v41, 15, v9
	v_lshl_add_u64 v[10:11], s[12:13], 2, v[2:3]
	v_lshl_add_u64 v[74:75], s[10:11], 1, v[4:5]
	v_mad_i64_i32 v[12:13], s[10:11], v9, s7, v[10:11]
	v_mad_i64_i32 v[14:15], s[10:11], v14, s7, v[10:11]
	v_mad_i64_i32 v[18:19], s[10:11], v16, s7, v[10:11]
	v_mad_i64_i32 v[22:23], s[10:11], v17, s7, v[10:11]
	v_mad_i64_i32 v[26:27], s[10:11], v20, s7, v[10:11]
	v_mad_i64_i32 v[30:31], s[10:11], v21, s7, v[10:11]
	v_mad_i64_i32 v[34:35], s[10:11], v24, s7, v[10:11]
	v_mad_i64_i32 v[38:39], s[10:11], v25, s7, v[10:11]
	v_mad_i64_i32 v[42:43], s[10:11], v28, s7, v[10:11]
	v_mad_i64_i32 v[46:47], s[10:11], v29, s7, v[10:11]
	v_mad_i64_i32 v[50:51], s[10:11], v32, s7, v[10:11]
	v_mad_i64_i32 v[54:55], s[10:11], v33, s7, v[10:11]
	v_mad_i64_i32 v[58:59], s[10:11], v36, s7, v[10:11]
	v_mad_i64_i32 v[62:63], s[10:11], v37, s7, v[10:11]
	v_mad_i64_i32 v[66:67], s[10:11], v40, s7, v[10:11]
	v_mad_i64_i32 v[70:71], s[10:11], v41, s7, v[10:11]
	global_load_dwordx4 v[10:13], v[12:13], off nt
	s_nop 0
	global_load_dwordx4 v[14:17], v[14:15], off nt
	s_nop 0
	global_load_dwordx4 v[18:21], v[18:19], off nt
	s_nop 0
	global_load_dwordx4 v[22:25], v[22:23], off nt
	s_nop 0
	global_load_dwordx4 v[26:29], v[26:27], off nt
	s_nop 0
	global_load_dwordx4 v[30:33], v[30:31], off nt
	s_nop 0
	global_load_dwordx4 v[34:37], v[34:35], off nt
	s_nop 0
	global_load_dwordx4 v[38:41], v[38:39], off nt
	s_nop 0
	global_load_dwordx4 v[42:45], v[42:43], off nt
	s_nop 0
	global_load_dwordx4 v[46:49], v[46:47], off nt
	s_nop 0
	global_load_dwordx4 v[50:53], v[50:51], off nt
	s_nop 0
	global_load_dwordx4 v[54:57], v[54:55], off nt
	s_nop 0
	global_load_dwordx4 v[58:61], v[58:59], off nt
	s_nop 0
	global_load_dwordx4 v[62:65], v[62:63], off nt
	s_nop 0
	global_load_dwordx4 v[66:69], v[66:67], off nt
	s_nop 0
	global_load_dwordx4 v[70:73], v[70:71], off nt
	v_add_u32_e32 v76, s12, v6
	v_ashrrev_i32_e32 v77, 31, v76
	v_add_u32_e32 v78, 8, v76
	v_add_u32_e32 v80, 16, v76
	v_add_u32_e32 v82, 24, v76
	v_add_u32_e32 v84, 32, v76
	v_add_u32_e32 v86, 40, v76
	v_add_u32_e32 v88, 48, v76
	v_add_u32_e32 v90, 56, v76
	v_lshlrev_b64 v[76:77], 13, v[76:77]
	v_ashrrev_i32_e32 v79, 31, v78
	v_ashrrev_i32_e32 v81, 31, v80
	v_ashrrev_i32_e32 v83, 31, v82
	v_ashrrev_i32_e32 v85, 31, v84
	v_ashrrev_i32_e32 v87, 31, v86
	v_ashrrev_i32_e32 v89, 31, v88
	v_ashrrev_i32_e32 v91, 31, v90
	v_lshl_add_u64 v[92:93], v[74:75], 0, v[76:77]
	v_lshlrev_b64 v[76:77], 13, v[78:79]
	v_lshlrev_b64 v[78:79], 13, v[80:81]
	v_lshlrev_b64 v[80:81], 13, v[82:83]
	v_lshlrev_b64 v[82:83], 13, v[84:85]
	v_lshlrev_b64 v[84:85], 13, v[86:87]
	v_lshlrev_b64 v[86:87], 13, v[88:89]
	v_lshlrev_b64 v[88:89], 13, v[90:91]
	v_lshl_add_u64 v[90:91], v[74:75], 0, v[76:77]
	v_lshl_add_u64 v[94:95], v[74:75], 0, v[78:79]
	v_lshl_add_u64 v[96:97], v[74:75], 0, v[80:81]
	v_lshl_add_u64 v[82:83], v[74:75], 0, v[82:83]
	v_lshl_add_u64 v[84:85], v[74:75], 0, v[84:85]
	v_lshl_add_u64 v[86:87], v[74:75], 0, v[86:87]
	v_lshl_add_u64 v[88:89], v[74:75], 0, v[88:89]
	s_add_i32 s8, s8, s6
	s_add_i32 s3, s3, s5
	s_cmpk_gt_i32 s8, 0x5fff
	s_waitcnt vmcnt(14)
	v_cvt_pk_bf16_f32 v10, v10, v14
	v_cvt_pk_bf16_f32 v14, v11, v15
	v_cvt_pk_bf16_f32 v74, v12, v16
	v_cvt_pk_bf16_f32 v78, v13, v17
	s_waitcnt vmcnt(12)
	v_cvt_pk_bf16_f32 v11, v18, v22
	s_waitcnt vmcnt(10)
	v_cvt_pk_bf16_f32 v12, v26, v30
	s_waitcnt vmcnt(8)
	v_cvt_pk_bf16_f32 v13, v34, v38
	v_cvt_pk_bf16_f32 v15, v19, v23
	v_cvt_pk_bf16_f32 v75, v20, v24
	v_cvt_pk_bf16_f32 v79, v21, v25
	v_cvt_pk_bf16_f32 v16, v27, v31
	v_cvt_pk_bf16_f32 v76, v28, v32
	v_cvt_pk_bf16_f32 v80, v29, v33
	s_waitcnt vmcnt(6)
	v_cvt_pk_bf16_f32 v18, v42, v46
	v_cvt_pk_bf16_f32 v17, v35, v39
	v_cvt_pk_bf16_f32 v77, v36, v40
	v_cvt_pk_bf16_f32 v81, v37, v41
	v_cvt_pk_bf16_f32 v22, v43, v47
	v_cvt_pk_bf16_f32 v26, v44, v48
	v_cvt_pk_bf16_f32 v30, v45, v49
	s_waitcnt vmcnt(4)
	v_cvt_pk_bf16_f32 v19, v50, v54
	v_cvt_pk_bf16_f32 v23, v51, v55
	v_cvt_pk_bf16_f32 v27, v52, v56
	v_cvt_pk_bf16_f32 v31, v53, v57
	s_waitcnt vmcnt(2)
	v_cvt_pk_bf16_f32 v20, v58, v62
	v_cvt_pk_bf16_f32 v24, v59, v63
	v_cvt_pk_bf16_f32 v28, v60, v64
	v_cvt_pk_bf16_f32 v32, v61, v65
	s_waitcnt vmcnt(0)
	v_cvt_pk_bf16_f32 v21, v66, v70
	v_cvt_pk_bf16_f32 v25, v67, v71
	v_cvt_pk_bf16_f32 v29, v68, v72
	v_cvt_pk_bf16_f32 v33, v69, v73
	ds_write_b128 v7, v[10:13]
	ds_write_b128 v7, v[18:21] offset:16
	ds_write_b128 v7, v[14:17] offset:144
	ds_write_b128 v7, v[22:25] offset:160
	ds_write_b128 v7, v[74:77] offset:288
	ds_write_b128 v7, v[26:29] offset:304
	ds_write_b128 v7, v[78:81] offset:432
	ds_write_b128 v7, v[30:33] offset:448
	s_waitcnt lgkmcnt(0)
	ds_read_b128 v[10:13], v8
	ds_read_b128 v[14:17], v8 offset:1152
	ds_read_b128 v[18:21], v8 offset:2304
	ds_read_b128 v[22:25], v8 offset:3456
	ds_read_b128 v[26:29], v8 offset:4608
	ds_read_b128 v[30:33], v8 offset:5760
	ds_read_b128 v[34:37], v8 offset:6912
	ds_read_b128 v[38:41], v8 offset:8064
	s_waitcnt lgkmcnt(7)
	global_store_dwordx4 v[92:93], v[10:13], off nt
	s_waitcnt lgkmcnt(6)
	global_store_dwordx4 v[90:91], v[14:17], off nt
	s_waitcnt lgkmcnt(5)
	global_store_dwordx4 v[94:95], v[18:21], off nt
	s_waitcnt lgkmcnt(4)
	global_store_dwordx4 v[96:97], v[22:25], off nt
	s_waitcnt lgkmcnt(3)
	global_store_dwordx4 v[82:83], v[26:29], off nt
	s_waitcnt lgkmcnt(2)
	global_store_dwordx4 v[84:85], v[30:33], off nt
	s_waitcnt lgkmcnt(1)
	global_store_dwordx4 v[86:87], v[34:37], off nt
	s_waitcnt lgkmcnt(0)
	global_store_dwordx4 v[88:89], v[38:41], off nt
	s_waitcnt lgkmcnt(0)
	s_cbranch_scc0 .LBB0_12

; #define LAS __attribute__((address_space(3)))
; DI void cv_finish(const CvJob& j, int idx, int lane, const f32x4 (&q0)[4], const f32x4 (&q1)[4], const f32x4 (&q2)[4], const f32x4 (&q3)[4], LAS uchar* scr) {
;     const float* W; int K, N, item; bf16* WT; const float* ks; cv_decode(j, idx, W, K, N, WT, ks, item);
;     const int nblk = N / 64, kb = item / nblk, nb = item % nblk, k0 = 64 * kb, n0 = 64 * nb, q = lane >> 4, c16 = lane & 15;
;     f32x4 v[16], kv[4];
;     if (ks) {
; #pragma unroll
;         for (int i = 0; i < 4; ++i) kv[i] = *(const f32x4*)(ks + k0 + 16 * q + 4 * i); }
;     else {
; #pragma unroll
;         for (int i = 0; i < 4; ++i) kv[i] = (f32x4){1.f, 1.f, 1.f, 1.f}; }
.LBB0_259:
	v_cvt_f32_u32_e32 v66, s87
	s_sub_i32 s89, 0, s87
	s_abs_i32 s88, s84
	s_ashr_i32 s37, s84, 31
	v_rcp_iflag_f32_e32 v66, v66
	s_nop 0
	v_mul_f32_e32 v66, 0x4f7ffffe, v66
	v_cvt_u32_f32_e32 v66, v66
	s_nop 0
	v_readfirstlane_b32 s90, v66
	s_mul_i32 s89, s89, s90
	s_mul_hi_u32 s89, s90, s89
	s_add_i32 s90, s90, s89
	s_mul_hi_u32 s89, s88, s90
	s_mul_i32 s90, s89, s87
	s_sub_i32 s88, s88, s90
	s_add_i32 s91, s89, 1
	s_sub_i32 s90, s88, s87
	s_cmp_ge_u32 s88, s87
	s_cselect_b32 s89, s91, s89
	s_cselect_b32 s88, s90, s88
	s_add_i32 s90, s89, 1
	s_cmp_ge_u32 s88, s87
	s_cselect_b32 s88, s90, s89
	s_xor_b32 s88, s88, s37
	s_sub_i32 s37, s88, s37
	s_lshl_b32 vcc_lo, s37, 6
	s_ashr_i32 vcc_hi, vcc_lo, 31
	s_cmp_eq_u64 s[78:79], 0
	s_cbranch_scc1 .LBB0_261
	s_lshl_b64 s[88:89], vcc, 2
	s_add_u32 s78, s78, s88
	s_addc_u32 s79, s79, s89
	v_lshlrev_b32_e32 v66, 2, v102
	global_load_dwordx4 v[78:81], v66, s[78:79] offset:48 nt
	global_load_dwordx4 v[74:77], v66, s[78:79] offset:32 nt
	global_load_dwordx4 v[70:73], v66, s[78:79] offset:16 nt
	s_nop 0
	global_load_dwordx4 v[66:69], v66, s[78:79] nt
	s_waitcnt vmcnt(3)
	v_mov_b32_e32 v134, v79
	v_mov_b32_e32 v82, v81
	s_waitcnt vmcnt(2)
	v_mov_b32_e32 v130, v75
	v_mov_b32_e32 v132, v77
	s_waitcnt vmcnt(1)
	v_mov_b32_e32 v126, v71
	v_mov_b32_e32 v128, v73
	s_waitcnt vmcnt(0)
	v_mov_b32_e32 v122, v67
	v_mov_b32_e32 v124, v69
	s_branch .LBB0_262

; #define LAS __attribute__((address_space(3)))
; DI unsigned pk2(float lo, float hi) { f32x2 v = {lo, hi}; bf16v2 b = __builtin_convertvector(v, bf16v2); return __builtin_bit_cast(unsigned, b); }
; DI void cv_finish(const CvJob& j, int idx, int lane, const f32x4 (&q0)[4], const f32x4 (&q1)[4], const f32x4 (&q2)[4], const f32x4 (&q3)[4], LAS uchar* scr) {
;     const float* W; int K, N, item; bf16* WT; const float* ks; cv_decode(j, idx, W, K, N, WT, ks, item);
;     const int nblk = N / 64, kb = item / nblk, nb = item % nblk, k0 = 64 * kb, n0 = 64 * nb, q = lane >> 4, c16 = lane & 15;
;     f32x4 v[16], kv[4];
;     if (ks) {
; #pragma unroll
;         for (int i = 0; i < 4; ++i) kv[i] = *(const f32x4*)(ks + k0 + 16 * q + 4 * i); }
;     else {
; #pragma unroll
;         for (int i = 0; i < 4; ++i) kv[i] = (f32x4){1.f, 1.f, 1.f, 1.f}; }
; #pragma unroll
;     for (int i = 0; i < 16; ++i) v[i] = (i < 4 ? q0[i & 3] : i < 8 ? q1[i & 3] : i < 12 ? q2[i & 3] : q3[i & 3]) * kv[i >> 2][i & 3];
; #pragma unroll
;     for (int jj = 0; jj < 4; ++jj) { u32x4 lo, hi;
;         lo.x = pk2(v[0][jj], v[1][jj]); lo.y = pk2(v[2][jj], v[3][jj]); lo.z = pk2(v[4][jj], v[5][jj]); lo.w = pk2(v[6][jj], v[7][jj]);
;         hi.x = pk2(v[8][jj], v[9][jj]); hi.y = pk2(v[10][jj], v[11][jj]); hi.z = pk2(v[12][jj], v[13][jj]); hi.w = pk2(v[14][jj], v[15][jj]);
;         LAS uchar* p = scr + (4 * c16 + jj) * TSTR + q * 32; *(LAS u32x4*)p = lo; *(LAS u32x4*)(p + 16) = hi; }
;     asm volatile("s_waitcnt lgkmcnt(0)" ::: "memory");
;     const int c = lane & 7, nr = lane >> 3;
; #pragma unroll
;     for (int hf = 0; hf < 2; ++hf) {
; #pragma unroll
;         for (int r = 4 * hf; r < 4 * hf + 4; ++r) { const int n = nr + 8 * r;
;             *(u32x4*)(WT + (size_t)(n0 + n) * K + k0 + 8 * c) = *(const LAS u32x4*)(scr + n * TSTR + c * 16); }
;         asm volatile("s_waitcnt lgkmcnt(0)" ::: "memory"); }
; }
.LBB0_262:
	v_pk_mul_f32 v[30:31], v[30:31], v[128:129] op_sel_hi:[1,0]
	v_pk_mul_f32 v[28:29], v[28:29], v[72:73] op_sel_hi:[1,0]
	v_pk_mul_f32 v[26:27], v[26:27], v[72:73] op_sel_hi:[1,0]
	v_pk_mul_f32 v[22:23], v[22:23], v[126:127] op_sel_hi:[1,0]
	v_pk_mul_f32 v[20:21], v[20:21], v[70:71] op_sel_hi:[1,0]
	v_pk_mul_f32 v[18:19], v[18:19], v[70:71] op_sel_hi:[1,0]
	v_pk_mul_f32 v[14:15], v[14:15], v[124:125] op_sel_hi:[1,0]
	v_pk_mul_f32 v[10:11], v[10:11], v[68:69] op_sel_hi:[1,0]
	v_pk_mul_f32 v[70:71], v[6:7], v[122:123] op_sel_hi:[1,0]
	v_pk_mul_f32 v[72:73], v[4:5], v[66:67] op_sel_hi:[1,0]
	v_pk_mul_f32 v[66:67], v[2:3], v[66:67] op_sel_hi:[1,0]
	s_waitcnt vmcnt(6)
	v_pk_mul_f32 v[62:63], v[62:63], v[80:81] op_sel_hi:[1,0]
	v_pk_mul_f32 v[58:59], v[58:59], v[134:135] op_sel_hi:[1,0]
	s_waitcnt vmcnt(5)
	v_pk_mul_f32 v[54:55], v[54:55], v[78:79] op_sel_hi:[1,0]
	v_pk_mul_f32 v[46:47], v[46:47], v[132:133] op_sel_hi:[1,0]
	v_pk_mul_f32 v[42:43], v[42:43], v[76:77] op_sel_hi:[1,0]
	v_pk_mul_f32 v[38:39], v[38:39], v[130:131] op_sel_hi:[1,0]
	v_pk_mul_f32 v[34:35], v[34:35], v[74:75] op_sel_hi:[1,0]
	s_waitcnt vmcnt(4)
	v_pk_mul_f32 v[50:51], v[50:51], v[82:83] op_sel_hi:[1,0]
	v_cvt_pk_bf16_f32 v2, v66, v70
	v_cvt_pk_bf16_f32 v3, v10, v14
	v_cvt_pk_bf16_f32 v4, v18, v22
	v_cvt_pk_bf16_f32 v5, v26, v30
	v_add_u32_e32 v10, v127, v129
	v_pk_mul_f32 v[32:33], v[32:33], v[128:129] op_sel_hi:[1,0]
	v_pk_mul_f32 v[24:25], v[24:25], v[126:127] op_sel_hi:[1,0]
	v_pk_mul_f32 v[16:17], v[16:17], v[124:125] op_sel_hi:[1,0]
	v_pk_mul_f32 v[12:13], v[12:13], v[68:69] op_sel_hi:[1,0]
	v_pk_mul_f32 v[68:69], v[8:9], v[122:123] op_sel_hi:[1,0]
	v_cvt_pk_bf16_f32 v6, v34, v38
	v_cvt_pk_bf16_f32 v7, v42, v46
	v_cvt_pk_bf16_f32 v8, v54, v58
	v_cvt_pk_bf16_f32 v9, v62, v50
	ds_write_b128 v10, v[2:5]
	ds_write_b128 v10, v[6:9] offset:16
	v_cvt_pk_bf16_f32 v2, v67, v71
	v_cvt_pk_bf16_f32 v3, v11, v15
	v_cvt_pk_bf16_f32 v4, v19, v23
	v_cvt_pk_bf16_f32 v5, v27, v31
	v_pk_mul_f32 v[64:65], v[64:65], v[80:81] op_sel_hi:[1,0]
	v_pk_mul_f32 v[60:61], v[60:61], v[134:135] op_sel_hi:[1,0]
	v_pk_mul_f32 v[56:57], v[56:57], v[78:79] op_sel_hi:[1,0]
	v_pk_mul_f32 v[48:49], v[48:49], v[132:133] op_sel_hi:[1,0]
	v_pk_mul_f32 v[44:45], v[44:45], v[76:77] op_sel_hi:[1,0]
	v_pk_mul_f32 v[40:41], v[40:41], v[130:131] op_sel_hi:[1,0]
	v_pk_mul_f32 v[36:37], v[36:37], v[74:75] op_sel_hi:[1,0]
	v_pk_mul_f32 v[52:53], v[52:53], v[82:83] op_sel_hi:[1,0]
	v_cvt_pk_bf16_f32 v6, v35, v39
	v_cvt_pk_bf16_f32 v7, v43, v47
	v_cvt_pk_bf16_f32 v8, v55, v59
	v_cvt_pk_bf16_f32 v9, v63, v51
	ds_write_b128 v10, v[2:5] offset:144
	ds_write_b128 v10, v[6:9] offset:160
	v_cvt_pk_bf16_f32 v2, v72, v68
	v_cvt_pk_bf16_f32 v3, v12, v16
	v_cvt_pk_bf16_f32 v4, v20, v24
	v_cvt_pk_bf16_f32 v5, v28, v32
	s_mul_i32 s37, s37, s87
	v_cvt_pk_bf16_f32 v6, v36, v40
	v_cvt_pk_bf16_f32 v7, v44, v48
	v_cvt_pk_bf16_f32 v8, v56, v60
	v_cvt_pk_bf16_f32 v9, v64, v52
	ds_write_b128 v10, v[2:5] offset:288
	ds_write_b128 v10, v[6:9] offset:304
	v_cvt_pk_bf16_f32 v2, v73, v69
	v_cvt_pk_bf16_f32 v3, v13, v17
	v_cvt_pk_bf16_f32 v4, v21, v25
	v_cvt_pk_bf16_f32 v5, v29, v33
	s_sub_i32 s37, s84, s37
	v_cvt_pk_bf16_f32 v6, v37, v41
	v_cvt_pk_bf16_f32 v7, v45, v49
	v_cvt_pk_bf16_f32 v8, v57, v61
	v_cvt_pk_bf16_f32 v9, v65, v53
	ds_write_b128 v10, v[2:5] offset:432
	ds_write_b128 v10, v[6:9] offset:448
	s_lshl_b32 s37, s37, 6
	s_waitcnt lgkmcnt(0)
	s_lshl_b64 s[78:79], vcc, 1
	v_add_u32_e32 v14, v133, v135
	s_add_u32 s40, s40, s78
	ds_read_b128 v[2:5], v14
	s_addc_u32 s41, s41, s79
	v_lshlrev_b32_e32 v82, 1, v92
	v_or_b32_e32 v6, s37, v131
	v_lshl_add_u64 v[10:11], s[40:41], 0, v[82:83]
	v_mad_i64_i32 v[6:7], s[40:41], s36, v6, 0
	v_lshl_add_u64 v[12:13], v[6:7], 1, v[10:11]
	ds_read_b128 v[6:9], v14 offset:1152
	s_waitcnt lgkmcnt(1)
	global_store_dwordx4 v[12:13], v[2:5], off nt
	s_nop 1
	v_or_b32_e32 v2, s37, v136
	v_mad_i64_i32 v[2:3], s[40:41], s36, v2, 0
	v_lshl_add_u64 v[2:3], v[2:3], 1, v[10:11]
	s_waitcnt lgkmcnt(0)
	global_store_dwordx4 v[2:3], v[6:9], off nt
	ds_read_b128 v[2:5], v14 offset:2304
	s_nop 0
	v_or_b32_e32 v6, s37, v137
	v_mad_i64_i32 v[6:7], s[40:41], s36, v6, 0
	v_lshl_add_u64 v[12:13], v[6:7], 1, v[10:11]
	ds_read_b128 v[6:9], v14 offset:3456
	s_waitcnt lgkmcnt(1)
	global_store_dwordx4 v[12:13], v[2:5], off nt
	s_nop 1
	v_or_b32_e32 v2, s37, v138
	v_mad_i64_i32 v[2:3], s[40:41], s36, v2, 0
	v_lshl_add_u64 v[2:3], v[2:3], 1, v[10:11]
	s_waitcnt lgkmcnt(0)
	global_store_dwordx4 v[2:3], v[6:9], off nt
	s_waitcnt lgkmcnt(0)
	ds_read_b128 v[2:5], v14 offset:4608
	s_nop 0
	v_or_b32_e32 v6, s37, v139
	v_mad_i64_i32 v[6:7], s[40:41], s36, v6, 0
	v_lshl_add_u64 v[12:13], v[6:7], 1, v[10:11]
	ds_read_b128 v[6:9], v14 offset:5760
	s_waitcnt lgkmcnt(1)
	global_store_dwordx4 v[12:13], v[2:5], off nt
	s_nop 1
	v_or_b32_e32 v2, s37, v140
	v_mad_i64_i32 v[2:3], s[40:41], s36, v2, 0
	v_lshl_add_u64 v[2:3], v[2:3], 1, v[10:11]
	s_waitcnt lgkmcnt(0)
	global_store_dwordx4 v[2:3], v[6:9], off nt
	ds_read_b128 v[2:5], v14 offset:6912
	s_nop 0
	v_or_b32_e32 v6, s37, v141
	v_mad_i64_i32 v[6:7], s[40:41], s36, v6, 0
	v_lshl_add_u64 v[12:13], v[6:7], 1, v[10:11]
	ds_read_b128 v[6:9], v14 offset:8064
	s_waitcnt lgkmcnt(1)
	global_store_dwordx4 v[12:13], v[2:5], off nt
	s_nop 1
	v_or_b32_e32 v2, s37, v142
	v_mad_i64_i32 v[2:3], s[36:37], s36, v2, 0
	v_lshl_add_u64 v[2:3], v[2:3], 1, v[10:11]
	s_waitcnt lgkmcnt(0)
	global_store_dwordx4 v[2:3], v[6:9], off nt
	s_waitcnt lgkmcnt(0)
	s_mov_b32 s36, s77

; #define LAS __attribute__((address_space(3)))
; DI float bf2f(unsigned h) { return __uint_as_float(h << 16); }
; DI void cv_issue_q(const CvJob& j, int idx, int lane, f32x4 (&v)[4], int r0) {
;     const float* W; int K, N, item; bf16* WT; const float* ks; cv_decode(j, idx, W, K, N, WT, ks, item);
;     const int nblk = N / 64, kb = item / nblk, nb = item % nblk, k0 = 64 * kb, n0 = 64 * nb, q = lane >> 4, c16 = lane & 15;
;     const char* ub = (const char*)(W + (size_t)(k0 + r0) * N + n0);
;     const unsigned vo = (unsigned)((16 * q) * N + 4 * c16) * 4u;
; #pragma unroll
;     for (int i = 0; i < 4; ++i) v[i] = *(const f32x4*)(ub + (size_t)i * N * 4 + vo);
; }
; DI void rglru_scan_unit(Frame& F, const Mix0Args& a, int u) {
;     ...
;         if constexpr (CV) { int idx = (n >> 2) * NGW + gw; idx = idx < CV_NIT ? idx : idx - CV_NIT;
;             if constexpr (CQ == 0) cv_issue_q(a.cv, idx, lane, cq0, 0); else if constexpr (CQ == 1) cv_issue_q(a.cv, idx, lane, cq1, 4); else if constexpr (CQ == 2) cv_issue_q(a.cv, idx, lane, cq2, 8); else cv_issue_q(a.cv, idx, lane, cq3, 12); }
;         const f32x4 zero4 = (f32x4){0.f, 0.f, 0.f, 0.f};
;         float av[4], uv[4]; float Aseg = 1.f, Hseg = 0.f;
;         { bf16x8 xf[4], waf[4], wxf[4]; unsigned xcr[4];
; #pragma unroll
;           for (int ks = 0; ks < 4; ++ks) { xf[ks] = *(const LAS bf16x8*)(XCc + (l0_ + fr) * S128 + ks * 64 + fq * 16);
;               waf[ks] = *(const LAS bf16x8*)(WAT + (16 * jtile + fr) * S128 + ks * 64 + fq * 16); wxf[ks] = *(const LAS bf16x8*)(WXT + (16 * jtile + fr) * S128 + ks * 64 + fq * 16); }
; #pragma unroll
;           for (int r = 0; r < 4; ++r) xcr[r] = *(const LAS unsigned short*)(XCc + (l0_ + 4 * fq + r) * S128 + (qq * 32 + jj) * 2);
;           f32x4 R = zero4, I = zero4;
; #pragma unroll
;           for (int ks = 0; ks < 4; ++ks) { R = __builtin_amdgcn_mfma_f32_16x16x32_bf16(xf[ks], waf[ks], R, 0, 0, 0); I = __builtin_amdgcn_mfma_f32_16x16x32_bf16(xf[ks], wxf[ks], I, 0, 0, 0); }
; #pragma unroll
;           for (int r = 0; r < 4; ++r) {
;               const float rr = fsigmoid(R[r] + bav), ig = fsigmoid(I[r] + bxv);
;               const float aa = fexp2(-sp8l2 * rr); const float om = __builtin_fmaf(-aa, aa, 1.0f);
;               av[r] = aa; uv[r] = __builtin_sqrtf(om) * (ig * bf2f(xcr[r]));
;               Hseg = aa * Hseg + uv[r]; Aseg *= aa; } }
.LBB0_269:
	s_lshr_b32 s79, s78, 6
	v_cvt_f32_u32_e32 v2, s79
	s_sub_i32 s90, 0, s79
	s_abs_i32 s89, s84
	s_ashr_i32 s88, s84, 31
	v_rcp_iflag_f32_e32 v2, v2
	v_mul_u32_u24_e32 v29, s78, v102
	v_or_b32_e32 v29, v29, v125
	v_lshlrev_b32_e32 v82, 2, v29
	v_mul_f32_e32 v2, 0x4f7ffffe, v2
	v_cvt_u32_f32_e32 v2, v2
	ds_read_b128 v[6:9], v103 offset:36864
	v_readfirstlane_b32 s91, v2
	s_mul_i32 s90, s90, s91
	s_mul_hi_u32 s90, s91, s90
	s_add_i32 s91, s91, s90
	s_mul_hi_u32 s90, s89, s91
	s_mul_i32 s91, s90, s79
	s_sub_i32 s89, s89, s91
	s_add_i32 vcc_lo, s90, 1
	s_sub_i32 s91, s89, s79
	s_cmp_ge_u32 s89, s79
	s_cselect_b32 s90, vcc_lo, s90
	s_cselect_b32 s89, s91, s89
	s_add_i32 s91, s90, 1
	ds_read_b128 v[2:5], v164
	s_cmp_ge_u32 s89, s79
	s_cselect_b32 s89, s91, s90
	s_xor_b32 s89, s89, s88
	s_sub_i32 s88, s89, s88
	s_mul_i32 s79, s88, s79
	s_lshl_b32 s88, s88, 6
	s_sub_i32 s79, s84, s79
	s_mul_hi_i32 s89, s88, s78
	s_mul_i32 s88, s88, s78
	s_lshl_b32 s90, s79, 6
	s_lshl_b64 s[88:89], s[88:89], 2
	s_add_u32 s79, s36, s88
	ds_read_b128 v[10:13], v103 offset:46080
	ds_read_b128 v[14:17], v164 offset:64
	ds_read_b128 v[30:33], v103 offset:36928
	ds_read_b128 v[38:41], v103 offset:46144
	ds_read_b128 v[42:45], v164 offset:128
	s_addc_u32 s84, s37, s89
	s_ashr_i32 s91, s90, 31
	s_waitcnt lgkmcnt(5)
	v_mfma_f32_16x16x32_bf16 v[6:9], v[2:5], v[6:9], 0
	s_lshl_b64 s[36:37], s[90:91], 2
	s_add_u32 s36, s79, s36
	s_addc_u32 s37, s84, s37
	s_waitcnt lgkmcnt(4)
	v_mfma_f32_16x16x32_bf16 v[10:13], v[2:5], v[10:13], 0
	global_load_dwordx4 v[2:5], v82, s[36:37] nt
	s_lshl_b32 s96, s78, 2
	v_lshl_add_u64 v[54:55], s[36:37], 0, v[82:83]
	s_waitcnt lgkmcnt(2)
	v_mfma_f32_16x16x32_bf16 v[6:9], v[14:17], v[30:33], v[6:9]
	ds_read_b128 v[30:33], v103 offset:36992
	ds_read_b128 v[46:49], v164 offset:192
	s_waitcnt lgkmcnt(3)
	v_mfma_f32_16x16x32_bf16 v[14:17], v[14:17], v[38:41], v[10:13]
	ds_read_b128 v[38:41], v103 offset:37056
	s_waitcnt lgkmcnt(2)
	v_mfma_f32_16x16x32_bf16 v[30:33], v[42:45], v[30:33], v[6:9]
	v_lshl_add_u64 v[10:11], v[54:55], 0, s[96:97]
	v_lshl_add_u64 v[58:59], v[10:11], 0, s[96:97]
	s_nop 0
	global_load_dwordx4 v[6:9], v[10:11], off nt
	s_nop 0
	global_load_dwordx4 v[10:13], v[58:59], off nt
	s_waitcnt lgkmcnt(0)
	v_mfma_f32_16x16x32_bf16 v[30:33], v[46:49], v[38:41], v[30:33]
	ds_read_b128 v[54:57], v103 offset:46208
	ds_read_b128 v[38:41], v103 offset:46272
	v_lshl_add_u64 v[58:59], v[58:59], 0, s[96:97]
	s_waitcnt lgkmcnt(1)
	v_mfma_f32_16x16x32_bf16 v[42:45], v[42:45], v[54:57], v[14:17]
	s_nop 2
	v_add_f32_e32 v29, v165, v30
	v_mul_f32_e32 v29, 0xbfb8aa3b, v29
	v_exp_f32_e32 v29, v29
	s_waitcnt lgkmcnt(0)
	v_mfma_f32_16x16x32_bf16 v[38:41], v[46:49], v[38:41], v[42:45]
	v_add_f32_e32 v31, v165, v31
	v_mul_f32_e32 v31, 0xbfb8aa3b, v31
	v_add_f32_e32 v14, 1.0, v29
	v_rcp_f32_e32 v29, v14
	v_exp_f32_e32 v31, v31
	global_load_dwordx4 v[14:17], v[58:59], off nt
	ds_read_u16 v42, v113
	ds_read_u16 v43, v113 offset:288
	ds_read_u16 v44, v113 offset:576
	ds_read_u16 v45, v113 offset:864
	v_mul_f32_e64 v29, v29, -v168
	v_exp_f32_e32 v70, v29
	v_add_f32_e32 v29, v167, v38
	v_mul_f32_e32 v29, 0xbfb8aa3b, v29
	v_exp_f32_e32 v29, v29
	v_fma_f32 v30, -v70, v70, 1.0
	v_mul_f32_e32 v38, 0x4f800000, v30
	v_cmp_gt_f32_e32 vcc, s42, v30
	v_add_f32_e32 v29, 1.0, v29
	v_rcp_f32_e32 v29, v29
	v_cndmask_b32_e32 v30, v30, v38, vcc
	v_sqrt_f32_e32 v38, v30
	v_add_f32_e32 v31, 1.0, v31
	v_rcp_f32_e32 v31, v31
	v_add_f32_e32 v32, v165, v32
	v_add_u32_e32 v46, -1, v38
	v_fma_f32 v47, -v46, v38, v30
	v_cmp_ge_f32_e64 s[36:37], 0, v47
	v_add_u32_e32 v47, 1, v38
	v_mul_f32_e32 v32, 0xbfb8aa3b, v32
	v_cndmask_b32_e64 v46, v38, v46, s[36:37]
	v_fma_f32 v38, -v47, v38, v30
	v_cmp_lt_f32_e64 s[36:37], 0, v38
	v_exp_f32_e32 v32, v32
	v_add_f32_e32 v33, v165, v33
	v_cndmask_b32_e64 v38, v46, v47, s[36:37]
	v_mul_f32_e32 v46, 0x37800000, v38
	v_cndmask_b32_e32 v38, v38, v46, vcc
	v_cmp_class_f32_e32 vcc, v30, v158
	v_add_f32_e32 v32, 1.0, v32
	v_rcp_f32_e32 v32, v32
	v_cndmask_b32_e32 v30, v38, v30, vcc
	s_waitcnt lgkmcnt(3)
	v_lshlrev_b32_e32 v38, 16, v42
	v_mul_f32_e32 v29, v29, v38
	v_mul_f32_e32 v71, v29, v30
	v_mul_f32_e64 v29, v31, -v168
	v_exp_f32_e32 v72, v29
	v_add_f32_e32 v29, v167, v39
	v_mul_f32_e32 v29, 0xbfb8aa3b, v29
	v_exp_f32_e32 v29, v29
	v_fma_f32 v30, -v72, v72, 1.0
	v_mul_f32_e32 v31, 0x4f800000, v30
	v_cmp_gt_f32_e32 vcc, s42, v30
	v_add_f32_e32 v29, 1.0, v29
	v_rcp_f32_e32 v29, v29
	v_cndmask_b32_e32 v30, v30, v31, vcc
	v_sqrt_f32_e32 v31, v30
	v_mul_f32_e32 v33, 0xbfb8aa3b, v33
	v_exp_f32_e32 v33, v33
	v_fma_f32 v38, 0, v70, v71
	v_add_u32_e32 v39, -1, v31
	v_fma_f32 v42, -v39, v31, v30
	v_cmp_ge_f32_e64 s[36:37], 0, v42
	v_add_u32_e32 v42, 1, v31
	v_add_f32_e32 v33, 1.0, v33
	v_cndmask_b32_e64 v39, v31, v39, s[36:37]
	v_fma_f32 v31, -v42, v31, v30
	v_cmp_lt_f32_e64 s[36:37], 0, v31
	v_rcp_f32_e32 v33, v33
	s_nop 0
	v_cndmask_b32_e64 v31, v39, v42, s[36:37]
	v_mul_f32_e32 v39, 0x37800000, v31
	v_cndmask_b32_e32 v31, v31, v39, vcc
	v_cmp_class_f32_e32 vcc, v30, v158
	s_nop 1
	v_cndmask_b32_e32 v30, v31, v30, vcc
	s_waitcnt lgkmcnt(2)
	v_lshlrev_b32_e32 v31, 16, v43
	v_mul_f32_e32 v29, v29, v31
	v_mul_f32_e32 v73, v29, v30
	v_mul_f32_e64 v30, v32, -v168
	v_exp_f32_e32 v74, v30
	v_add_f32_e32 v30, v167, v40
	v_mul_f32_e32 v30, 0xbfb8aa3b, v30
	v_exp_f32_e32 v30, v30
	v_fma_f32 v31, -v74, v74, 1.0
	v_mul_f32_e32 v32, 0x4f800000, v31
	v_cmp_gt_f32_e32 vcc, s42, v31
	v_add_f32_e32 v30, 1.0, v30
	v_rcp_f32_e32 v30, v30
	v_cndmask_b32_e32 v31, v31, v32, vcc
	v_sqrt_f32_e32 v32, v31
	v_fma_f32 v29, v72, v38, v73
	v_mul_f32_e32 v38, v70, v72
	v_add_u32_e32 v39, -1, v32
	v_fma_f32 v40, -v39, v32, v31
	v_cmp_ge_f32_e64 s[36:37], 0, v40
	v_add_u32_e32 v40, 1, v32
	s_nop 0
	v_cndmask_b32_e64 v39, v32, v39, s[36:37]
	v_fma_f32 v32, -v40, v32, v31
	v_cmp_lt_f32_e64 s[36:37], 0, v32
	s_nop 1
	v_cndmask_b32_e64 v32, v39, v40, s[36:37]
	v_mul_f32_e32 v39, 0x37800000, v32
	v_cndmask_b32_e32 v32, v32, v39, vcc
	v_cmp_class_f32_e32 vcc, v31, v158
	s_nop 1
	v_cndmask_b32_e32 v31, v32, v31, vcc
	s_waitcnt lgkmcnt(1)
; #define LAS __attribute__((address_space(3)))
; DI float bf2f(unsigned h) { return __uint_as_float(h << 16); }
; DI unsigned pk2(float lo, float hi) { f32x2 v = {lo, hi}; bf16v2 b = __builtin_convertvector(v, bf16v2); return __builtin_bit_cast(unsigned, b); }
; DI float fsilu(float x) { return x * fsigmoid(x); }
; #define LDS_BAR() do { asm volatile("s_waitcnt lgkmcnt(0)" ::: "memory"); __builtin_amdgcn_s_barrier(); asm volatile("" ::: "memory"); } while (0)
; DI void rglru_scan_unit(Frame& F, const Mix0Args& a, int u) {
;     ...
;         const int sgi = ltile * 4 + fq;
;         SEGA[jj * 20 + sgi] = Aseg; SEGH[jj * 20 + sgi] = Hseg;
;         LDS_BAR();
;         float carry = HPREV[jj * 20 + (n & 1)]; float sa[15], sh[15];
;         { f32x4 a4[4], h4[4];
; #pragma unroll
;           for (int i = 0; i < 4; ++i) { a4[i] = *(const LAS f32x4*)(SEGA + jj * 20 + 4 * i); h4[i] = *(const LAS f32x4*)(SEGH + jj * 20 + 4 * i); }
; #pragma unroll
;           for (int s = 0; s < 15; ++s) { sa[s] = a4[s >> 2][s & 3]; sh[s] = h4[s >> 2][s & 3]; } }
; #pragma unroll
;         for (int s = 0; s < 15; ++s) carry = (s < sgi) ? sa[s] * carry + sh[s] : carry;
; #pragma unroll
;         for (int r = 0; r < 4; ++r) { carry = av[r] * carry + uv[r];
;             const float o = carry * fsilu(bf2f(gb_cur[r]));
;             obcol[(row0 + l0_ + 4 * fq + r) * a.out_ld] = (bf16)(pk2(o, 0.f) & 0xffffu); }
;         if (sgi == 15) HPREV[jj * 20 + ((n + 1) & 1)] = carry;
	v_lshlrev_b32_e32 v32, 16, v44
	v_mul_f32_e32 v30, v30, v32
	v_mul_f32_e32 v75, v30, v31
	v_fma_f32 v30, v74, v29, v75
	v_mul_f32_e64 v29, v33, -v168
	v_exp_f32_e32 v76, v29
	v_add_f32_e32 v29, v167, v41
	v_mul_f32_e32 v29, 0xbfb8aa3b, v29
	v_exp_f32_e32 v29, v29
	v_fma_f32 v31, -v76, v76, 1.0
	v_mul_f32_e32 v32, 0x4f800000, v31
	v_cmp_gt_f32_e32 vcc, s42, v31
	v_mul_f32_e32 v33, v74, v38
	v_add_f32_e32 v29, 1.0, v29
	v_cndmask_b32_e32 v31, v31, v32, vcc
	v_sqrt_f32_e32 v32, v31
	v_rcp_f32_e32 v29, v29
	v_add_u32_e32 v38, -1, v32
	v_fma_f32 v39, -v38, v32, v31
	v_cmp_ge_f32_e64 s[36:37], 0, v39
	v_add_u32_e32 v39, 1, v32
	s_nop 0
	v_cndmask_b32_e64 v38, v32, v38, s[36:37]
	v_fma_f32 v32, -v39, v32, v31
	v_cmp_lt_f32_e64 s[36:37], 0, v32
	s_nop 1
	v_cndmask_b32_e64 v32, v38, v39, s[36:37]
	v_mul_f32_e32 v38, 0x37800000, v32
	v_cndmask_b32_e32 v32, v32, v38, vcc
	v_cmp_class_f32_e32 vcc, v31, v158
	s_mov_b32 s36, 0x25300000
	s_nop 0
	v_cndmask_b32_e32 v31, v32, v31, vcc
	s_waitcnt lgkmcnt(0)
	v_lshlrev_b32_e32 v32, 16, v45
	v_mul_f32_e32 v29, v29, v32
	v_mul_f32_e32 v29, v29, v31
	v_fma_f32 v30, v76, v30, v29
	v_mul_f32_e32 v31, v76, v33
	ds_write2st64_b32 v150, v31, v30 offset0:216 offset1:226
	s_waitcnt lgkmcnt(0)
	s_barrier
	ds_read_b32 v77, v149 offset:55360
	ds_read_b128 v[30:33], v149 offset:57856
	ds_read_b128 v[38:41], v149 offset:57872
	ds_read_b128 v[42:45], v149 offset:57888
	ds_read_b128 v[46:49], v149 offset:55296
	ds_read_b128 v[54:57], v149 offset:55312
	ds_read_b128 v[58:61], v149 offset:55328
	ds_read_b128 v[62:65], v149 offset:55344
	ds_read_b128 v[66:69], v149 offset:57904
	s_waitcnt lgkmcnt(4)
	v_fma_f32 v30, v77, v46, v30
	v_cndmask_b32_e64 v30, v30, v77, s[10:11]
	v_fma_f32 v31, v47, v30, v31
	v_cndmask_b32_e64 v30, v30, v31, s[12:13]
	v_fma_f32 v31, v48, v30, v32
	v_cndmask_b32_e64 v30, v30, v31, s[14:15]
	v_fmac_f32_e32 v33, v49, v30
	v_cndmask_b32_e64 v30, v33, v30, s[0:1]
	s_waitcnt lgkmcnt(3)
	v_fma_f32 v31, v54, v30, v38
	v_cndmask_b32_e64 v30, v30, v31, s[16:17]
	v_fma_f32 v31, v55, v30, v39
	v_cndmask_b32_e64 v30, v30, v31, s[18:19]
	v_fma_f32 v31, v56, v30, v40
	v_cndmask_b32_e64 v30, v30, v31, s[20:21]
	v_fmac_f32_e32 v41, v57, v30
	v_cndmask_b32_e64 v30, v30, v41, s[38:39]
	s_waitcnt lgkmcnt(2)
	v_fma_f32 v31, v58, v30, v42
	v_cndmask_b32_e64 v30, v30, v31, s[22:23]
	v_fma_f32 v31, v59, v30, v43
	v_cndmask_b32_e64 v30, v30, v31, s[24:25]
	v_fma_f32 v31, v60, v30, v44
	v_cndmask_b32_e64 v30, v30, v31, s[26:27]
	v_lshlrev_b32_e32 v32, 16, v181
	v_fmac_f32_e32 v45, v61, v30
	v_mul_f32_e32 v33, 0xbfb8aa3b, v32
	v_cndmask_b32_e64 v30, v30, v45, s[4:5]
	v_exp_f32_e32 v33, v33
	s_waitcnt lgkmcnt(0)
	v_fma_f32 v31, v62, v30, v66
	v_cndmask_b32_e64 v30, v30, v31, s[28:29]
	v_fma_f32 v31, v63, v30, v67
	v_cndmask_b32_e64 v30, v30, v31, s[30:31]
	v_add_f32_e32 v31, 1.0, v33
	v_rcp_f32_e32 v31, v31
	v_fmac_f32_e32 v68, v64, v30
	v_cndmask_b32_e64 v30, v30, v68, s[34:35]
	v_fmac_f32_e32 v71, v70, v30
	v_mul_f32_e32 v30, v31, v32
	v_mul_f32_e32 v30, v30, v71
	v_lshlrev_b32_e32 v33, 16, v180
	v_cvt_pk_bf16_f32 v32, v30, s0
	v_mul_f32_e32 v30, 0xbfb8aa3b, v33
	v_exp_f32_e32 v38, v30
	v_lshl_add_u64 v[66:67], v[116:117], 0, s[8:9]
	v_add_co_u32_e32 v30, vcc, s36, v66
	v_fmac_f32_e32 v73, v72, v71
	s_nop 0
	v_addc_co_u32_e32 v31, vcc, 0, v67, vcc
	global_store_short v[30:31], v32, off
	v_add_f32_e32 v30, 1.0, v38
	v_rcp_f32_e32 v30, v30
	v_lshlrev_b32_e32 v32, 16, v179
	v_mul_f32_e32 v31, 0xbfb8aa3b, v32
	v_exp_f32_e32 v31, v31
	v_mul_f32_e32 v30, v30, v33
	v_mul_f32_e32 v30, v30, v73
	v_cvt_pk_bf16_f32 v33, v30, s0
	v_add_f32_e32 v30, 1.0, v31
	v_rcp_f32_e32 v38, v30
	s_mov_b32 s36, 0x2530c000
	v_add_co_u32_e32 v30, vcc, s36, v66
	v_fmac_f32_e32 v75, v74, v73
	s_nop 0
	v_addc_co_u32_e32 v31, vcc, 0, v67, vcc
	global_store_short v[30:31], v33, off
	v_mul_f32_e32 v30, v38, v32
	v_lshlrev_b32_e32 v32, 16, v178
	v_mul_f32_e32 v31, 0xbfb8aa3b, v32
	v_exp_f32_e32 v31, v31
	v_mul_f32_e32 v30, v30, v75
	s_mov_b32 s36, 0x25318000
	v_cvt_pk_bf16_f32 v33, v30, s0
	v_add_f32_e32 v31, 1.0, v31
	v_rcp_f32_e32 v38, v31
	v_add_co_u32_e32 v30, vcc, s36, v66
	v_fmac_f32_e32 v29, v76, v75
	s_nop 0
	v_addc_co_u32_e32 v31, vcc, 0, v67, vcc
	global_store_short v[30:31], v33, off
	v_mul_f32_e32 v30, v38, v32
	v_mul_f32_e32 v30, v30, v29
	v_cvt_pk_bf16_f32 v32, v30, s0
	s_mov_b64 s[100:101], 0x25324000
	v_lshl_add_u64 v[30:31], v[66:67], 0, s[100:101]
	global_store_short v[30:31], v32, off
	s_and_saveexec_b64 s[36:37], s[34:35]
	ds_write_b32 v149, v29 offset:55364
	s_or_b64 exec, exec, s[36:37]
	s_waitcnt vmcnt(22)
	v_lshlrev_b32_e32 v30, 16, v18
	v_and_b32_e32 v31, 0xffff0000, v18
	v_pk_fma_f32 v[30:31], v[104:105], v[30:31], v[100:101]
	s_waitcnt vmcnt(21)
	v_lshlrev_b32_e32 v18, 16, v19
	v_and_b32_e32 v19, 0xffff0000, v19
	v_pk_fma_f32 v[30:31], v[106:107], v[18:19], v[30:31]
	s_waitcnt vmcnt(20)
	v_lshlrev_b32_e32 v32, 16, v20
	v_and_b32_e32 v33, 0xffff0000, v20
	v_pk_fma_f32 v[30:31], v[108:109], v[32:33], v[30:31]
	s_waitcnt vmcnt(19)
	v_lshlrev_b32_e32 v20, 16, v21
	v_and_b32_e32 v21, 0xffff0000, v21
	v_pk_fma_f32 v[18:19], v[104:105], v[18:19], v[100:101]
	v_pk_fma_f32 v[30:31], v[110:111], v[20:21], v[30:31]
	v_pk_fma_f32 v[18:19], v[106:107], v[32:33], v[18:19]
	v_cvt_pk_bf16_f32 v29, v30, v31
	v_pk_fma_f32 v[18:19], v[108:109], v[20:21], v[18:19]
	s_waitcnt vmcnt(18)
; #define LAS __attribute__((address_space(3)))
; #define LDS_BAR() do { asm volatile("s_waitcnt lgkmcnt(0)" ::: "memory"); __builtin_amdgcn_s_barrier(); asm volatile("" ::: "memory"); } while (0)
; #define RG_LOAD(n_) do { const long r0_ = (long)rowbase + (long)(n_) * 64; \
;         _Pragma("unroll") for (int i = 0; i < 11; ++i) xr[i] = ((n_) == 0 && 8 * rg - 3 + i < 0) ? 0u : *(const unsigned*)(xcol + (size_t)(r0_ + 8 * rg - 3 + i) * N1); } while (0)
; #define RG_LOADG(n_) do { const long r0_ = (long)rowbase + (long)(n_) * 64; \
;         _Pragma("unroll") for (int i = 0; i < 4; ++i) gbr[i] = *(const unsigned short*)(gbcol + (size_t)(r0_ + l0_ + 4 * fq + i) * N1); } while (0)
; DI void rglru_scan_unit(Frame& F, const Mix0Args& a, int u) {
;     ...
;     RG_LOAD(0);
;     RG_STAGE(XC0);
;     unsigned gb_cur[4];
;     RG_LOAD(1); RG_LOADG(0);
;     LDS_BAR();
;     const int nsl = cv_on ? min(NCH / 4, max(0, (CV_NIT - 8 * F.vcu + NGW - 1) / NGW)) : 0;
;     auto rg_step = [&](int n, auto cvt) __attribute__((always_inline)) {
;         constexpr int CQ = decltype(cvt)::value; constexpr bool CV = CQ >= 0;
;         const size_t row0 = rowbase + (size_t)n * 64;
;         LAS uchar* XCc = XC0 + (n & 1) * 64 * S128; LAS uchar* XCn = XC0 + ((n + 1) & 1) * 64 * S128;
;         LAS float* SEGA = SEG0 + (n & 1) * 1280; LAS float* SEGH = SEGA + 640;
; #pragma unroll
;         for (int i = 0; i < 4; ++i) gb_cur[i] = gbr[i];
;         if (n + 1 < NCH) RG_STAGE(XCn);
;         if constexpr (CQ == 0) { if (n > 0) { const int ip = ((n >> 2) - 1) * NGW + gw; if (ip < CV_NIT) cv_finish(a.cv, ip, lane, cq0, cq1, cq2, cq3, CVS); } }
;         if (n + 2 < NCH) RG_LOAD(n + 2);
;         if (n + 1 < NCH) RG_LOADG(n + 1);
;         if constexpr (CV) { int idx = (n >> 2) * NGW + gw; idx = idx < CV_NIT ? idx : idx - CV_NIT;
;             if constexpr (CQ == 0) cv_issue_q(a.cv, idx, lane, cq0, 0); else if constexpr (CQ == 1) cv_issue_q(a.cv, idx, lane, cq1, 4); else if constexpr (CQ == 2) cv_issue_q(a.cv, idx, lane, cq2, 8); else cv_issue_q(a.cv, idx, lane, cq3, 12); }
	v_lshlrev_b32_e32 v30, 16, v22
	v_and_b32_e32 v31, 0xffff0000, v22
	v_pk_fma_f32 v[18:19], v[110:111], v[30:31], v[18:19]
	s_waitcnt vmcnt(17)
	v_lshlrev_b32_e32 v22, 16, v23
	v_cvt_pk_bf16_f32 v18, v18, v19
	ds_write2_b32 v123, v29, v18 offset1:72
	v_pk_fma_f32 v[18:19], v[104:105], v[32:33], v[100:101]
	v_and_b32_e32 v23, 0xffff0000, v23
	v_pk_fma_f32 v[18:19], v[106:107], v[20:21], v[18:19]
	v_add_u32_e32 v54, 0x400, v123
	v_pk_fma_f32 v[18:19], v[108:109], v[30:31], v[18:19]
	s_mov_b32 s36, 0x25be4000
	v_pk_fma_f32 v[18:19], v[110:111], v[22:23], v[18:19]
	s_nop 0
	v_cvt_pk_bf16_f32 v29, v18, v19
	v_pk_fma_f32 v[18:19], v[104:105], v[20:21], v[100:101]
	s_waitcnt vmcnt(16)
	v_lshlrev_b32_e32 v20, 16, v24
	v_pk_fma_f32 v[18:19], v[106:107], v[30:31], v[18:19]
	v_and_b32_e32 v21, 0xffff0000, v24
	v_pk_fma_f32 v[18:19], v[108:109], v[22:23], v[18:19]
	s_nop 0
	v_pk_fma_f32 v[18:19], v[110:111], v[20:21], v[18:19]
	s_nop 0
	v_cvt_pk_bf16_f32 v18, v18, v19
	ds_write2_b32 v123, v29, v18 offset0:144 offset1:216
	v_pk_fma_f32 v[18:19], v[104:105], v[30:31], v[100:101]
	s_waitcnt vmcnt(15)
	v_lshlrev_b32_e32 v30, 16, v27
	v_pk_fma_f32 v[18:19], v[106:107], v[22:23], v[18:19]
	v_and_b32_e32 v31, 0xffff0000, v27
	v_pk_fma_f32 v[18:19], v[108:109], v[20:21], v[18:19]
	s_nop 0
	v_pk_fma_f32 v[18:19], v[110:111], v[30:31], v[18:19]
	s_nop 0
	v_cvt_pk_bf16_f32 v24, v18, v19
	v_pk_fma_f32 v[18:19], v[104:105], v[22:23], v[100:101]
	s_waitcnt vmcnt(14)
	v_lshlrev_b32_e32 v22, 16, v25
	v_pk_fma_f32 v[18:19], v[106:107], v[20:21], v[18:19]
	v_and_b32_e32 v23, 0xffff0000, v25
	v_pk_fma_f32 v[18:19], v[108:109], v[30:31], v[18:19]
	s_nop 0
	v_pk_fma_f32 v[18:19], v[110:111], v[22:23], v[18:19]
	s_nop 0
	v_cvt_pk_bf16_f32 v18, v18, v19
	ds_write2_b32 v54, v24, v18 offset0:32 offset1:104
	v_pk_fma_f32 v[18:19], v[104:105], v[20:21], v[100:101]
	s_waitcnt vmcnt(13)
	v_lshlrev_b32_e32 v20, 16, v26
	v_pk_fma_f32 v[18:19], v[106:107], v[30:31], v[18:19]
	v_and_b32_e32 v21, 0xffff0000, v26
	v_pk_fma_f32 v[18:19], v[108:109], v[22:23], v[18:19]
	s_nop 0
	v_pk_fma_f32 v[18:19], v[110:111], v[20:21], v[18:19]
	s_nop 0
	v_cvt_pk_bf16_f32 v24, v18, v19
	v_pk_fma_f32 v[18:19], v[104:105], v[30:31], v[100:101]
	s_nop 0
	v_pk_fma_f32 v[18:19], v[106:107], v[22:23], v[18:19]
	s_nop 0
	v_pk_fma_f32 v[18:19], v[108:109], v[20:21], v[18:19]
	s_waitcnt vmcnt(12)
	v_lshlrev_b32_e32 v20, 16, v28
	v_and_b32_e32 v21, 0xffff0000, v28
	v_pk_fma_f32 v[18:19], v[110:111], v[20:21], v[18:19]
	s_nop 0
	v_cvt_pk_bf16_f32 v18, v18, v19
	ds_write2_b32 v54, v24, v18 offset0:176 offset1:248
	v_add_co_u32_e32 v18, vcc, s36, v50
	s_mov_b32 s36, 0x25bf0000
	s_nop 0
	v_addc_co_u32_e32 v19, vcc, 0, v51, vcc
	global_load_dword v130, v[18:19], off
	v_add_co_u32_e32 v18, vcc, s36, v50
	s_mov_b32 s36, 0x25bfc000
	s_nop 0
	v_addc_co_u32_e32 v19, vcc, 0, v51, vcc
	global_load_dword v132, v[18:19], off
	v_add_co_u32_e32 v18, vcc, s36, v50
	s_mov_b32 s36, 0x25c08000
	s_nop 0
	v_addc_co_u32_e32 v19, vcc, 0, v51, vcc
	global_load_dword v134, v[18:19], off
	v_add_co_u32_e32 v18, vcc, s36, v50
	s_mov_b32 s36, 0x25c14000
	s_nop 0
	v_addc_co_u32_e32 v19, vcc, 0, v51, vcc
	global_load_dword v169, v[18:19], off
	v_add_co_u32_e32 v18, vcc, s36, v50
	s_mov_b32 s36, 0x25c20000
	s_nop 0
	v_addc_co_u32_e32 v19, vcc, 0, v51, vcc
	global_load_dword v170, v[18:19], off
	v_add_co_u32_e32 v18, vcc, s36, v50
	s_mov_b32 s36, 0x25c2c000
	s_nop 0
	v_addc_co_u32_e32 v19, vcc, 0, v51, vcc
	global_load_dword v171, v[18:19], off
	v_add_co_u32_e32 v18, vcc, s36, v50
	s_mov_b32 s36, 0x25c38000
	s_nop 0
	v_addc_co_u32_e32 v19, vcc, 0, v51, vcc
	global_load_dword v172, v[18:19], off
	v_add_co_u32_e32 v18, vcc, s36, v50
	s_mov_b32 s36, 0x25c44000
	s_nop 0
	v_addc_co_u32_e32 v19, vcc, 0, v51, vcc
	global_load_dword v173, v[18:19], off
	v_add_co_u32_e32 v18, vcc, s36, v50
	s_mov_b32 s36, 0x25c50000
	s_nop 0
	v_addc_co_u32_e32 v19, vcc, 0, v51, vcc
	global_load_dword v174, v[18:19], off
	v_add_co_u32_e32 v18, vcc, s36, v50
	s_mov_b32 s36, 0x25c5c000
	s_nop 0
	v_addc_co_u32_e32 v19, vcc, 0, v51, vcc
	global_load_dword v175, v[18:19], off
	v_add_co_u32_e32 v18, vcc, s36, v50
	s_mov_b32 s36, 0x2590a000
	s_nop 0
	v_addc_co_u32_e32 v19, vcc, 0, v51, vcc
	global_load_dword v176, v[18:19], off
	v_add_co_u32_e32 v18, vcc, s36, v52
	s_nop 1
	v_addc_co_u32_e32 v19, vcc, 0, v53, vcc
	global_load_ushort v58, v[18:19], off
	s_mov_b64 s[100:101], 0x25916000
	v_lshl_add_u64 v[18:19], v[52:53], 0, s[100:101]
	global_load_ushort v56, v[18:19], off
	s_mov_b64 s[100:101], 0x25922000
	v_lshl_add_u64 v[18:19], v[52:53], 0, s[100:101]
	global_load_ushort v55, v[18:19], off
	s_mov_b64 s[100:101], 0x2592e000
	v_lshl_add_u64 v[18:19], v[52:53], 0, s[100:101]
	global_load_ushort v57, v[18:19], off
	v_cndmask_b32_e64 v18, 0, 1, s[40:41]
	v_cmp_ne_u32_e64 s[36:37], 1, v18
	s_andn2_b64 vcc, exec, s[40:41]
	s_cbranch_vccnz .LBB0_274
	s_cmpk_gt_u32 s87, 0x687f
	s_cbranch_scc0 .LBB0_275
	s_add_i32 s84, s87, 0xffff9780
	s_mov_b64 s[40:41], s[52:53]
	s_movk_i32 s78, 0x1000
	s_cbranch_execz .LBB0_276
	s_branch .LBB0_277

; #define LAS __attribute__((address_space(3)))
; DI float bf2f(unsigned h) { return __uint_as_float(h << 16); }
; DI void cv_issue_q(const CvJob& j, int idx, int lane, f32x4 (&v)[4], int r0) {
;     const float* W; int K, N, item; bf16* WT; const float* ks; cv_decode(j, idx, W, K, N, WT, ks, item);
;     const int nblk = N / 64, kb = item / nblk, nb = item % nblk, k0 = 64 * kb, n0 = 64 * nb, q = lane >> 4, c16 = lane & 15;
;     const char* ub = (const char*)(W + (size_t)(k0 + r0) * N + n0);
;     const unsigned vo = (unsigned)((16 * q) * N + 4 * c16) * 4u;
; #pragma unroll
;     for (int i = 0; i < 4; ++i) v[i] = *(const f32x4*)(ub + (size_t)i * N * 4 + vo);
; }
; DI void rglru_scan_unit(Frame& F, const Mix0Args& a, int u) {
;     ...
;         if constexpr (CV) { int idx = (n >> 2) * NGW + gw; idx = idx < CV_NIT ? idx : idx - CV_NIT;
;             if constexpr (CQ == 0) cv_issue_q(a.cv, idx, lane, cq0, 0); else if constexpr (CQ == 1) cv_issue_q(a.cv, idx, lane, cq1, 4); else if constexpr (CQ == 2) cv_issue_q(a.cv, idx, lane, cq2, 8); else cv_issue_q(a.cv, idx, lane, cq3, 12); }
;         const f32x4 zero4 = (f32x4){0.f, 0.f, 0.f, 0.f};
;         float av[4], uv[4]; float Aseg = 1.f, Hseg = 0.f;
;         { bf16x8 xf[4], waf[4], wxf[4]; unsigned xcr[4];
; #pragma unroll
;           for (int ks = 0; ks < 4; ++ks) { xf[ks] = *(const LAS bf16x8*)(XCc + (l0_ + fr) * S128 + ks * 64 + fq * 16);
;               waf[ks] = *(const LAS bf16x8*)(WAT + (16 * jtile + fr) * S128 + ks * 64 + fq * 16); wxf[ks] = *(const LAS bf16x8*)(WXT + (16 * jtile + fr) * S128 + ks * 64 + fq * 16); }
; #pragma unroll
;           for (int r = 0; r < 4; ++r) xcr[r] = *(const LAS unsigned short*)(XCc + (l0_ + 4 * fq + r) * S128 + (qq * 32 + jj) * 2);
;           f32x4 R = zero4, I = zero4;
; #pragma unroll
;           for (int ks = 0; ks < 4; ++ks) { R = __builtin_amdgcn_mfma_f32_16x16x32_bf16(xf[ks], waf[ks], R, 0, 0, 0); I = __builtin_amdgcn_mfma_f32_16x16x32_bf16(xf[ks], wxf[ks], I, 0, 0, 0); }
; #pragma unroll
;           for (int r = 0; r < 4; ++r) {
;               const float rr = fsigmoid(R[r] + bav), ig = fsigmoid(I[r] + bxv);
;               const float aa = fexp2(-sp8l2 * rr); const float om = __builtin_fmaf(-aa, aa, 1.0f);
;               av[r] = aa; uv[r] = __builtin_sqrtf(om) * (ig * bf2f(xcr[r]));
;               Hseg = aa * Hseg + uv[r]; Aseg *= aa; } }
.LBB0_277:
	s_lshr_b32 s79, s78, 6
	v_cvt_f32_u32_e32 v18, s79
	s_sub_i32 s90, 0, s79
	s_abs_i32 s89, s84
	s_ashr_i32 s88, s84, 31
	v_rcp_iflag_f32_e32 v18, v18
	v_mul_u32_u24_e32 v42, s78, v102
	v_or_b32_e32 v42, v42, v125
	v_lshlrev_b32_e32 v82, 2, v42
	v_mul_f32_e32 v18, 0x4f7ffffe, v18
	v_cvt_u32_f32_e32 v18, v18
	s_waitcnt vmcnt(26)
	v_lshlrev_b32_e32 v37, 16, v37
	s_waitcnt vmcnt(24)
	v_lshlrev_b32_e32 v34, 16, v34
	ds_read_b128 v[22:25], v103 offset:36864
	v_readfirstlane_b32 s91, v18
	s_mul_i32 s90, s90, s91
	s_mul_hi_u32 s90, s91, s90
	s_add_i32 s91, s91, s90
	s_mul_hi_u32 s90, s89, s91
	s_mul_i32 s91, s90, s79
	s_sub_i32 s89, s89, s91
	s_add_i32 vcc_lo, s90, 1
	s_sub_i32 s91, s89, s79
	s_cmp_ge_u32 s89, s79
	s_cselect_b32 s90, vcc_lo, s90
	s_cselect_b32 s89, s91, s89
	s_add_i32 s91, s90, 1
	s_cmp_ge_u32 s89, s79
	ds_read_b128 v[18:21], v164 offset:18432
	s_cselect_b32 s89, s91, s90
	s_xor_b32 s89, s89, s88
	s_sub_i32 s88, s89, s88
	s_mul_i32 s79, s88, s79
	s_lshl_b32 s88, s88, 6
	s_sub_i32 s79, s84, s79
	s_or_b32 s84, s88, 4
	s_mul_hi_i32 s91, s84, s78
	s_mul_i32 s90, s84, s78
	s_lshl_b32 s88, s79, 6
	s_lshl_b64 s[90:91], s[90:91], 2
	s_add_u32 s79, s40, s90
	ds_read_b128 v[26:29], v103 offset:46080
	ds_read_b128 v[30:33], v164 offset:18496
	ds_read_b128 v[38:41], v103 offset:36928
	ds_read_b128 v[42:45], v103 offset:46144
	ds_read_b128 v[46:49], v164 offset:18560
	s_addc_u32 s84, s41, s91
	s_ashr_i32 s89, s88, 31
	s_waitcnt lgkmcnt(5)
	v_mfma_f32_16x16x32_bf16 v[22:25], v[18:21], v[22:25], 0
	s_lshl_b64 s[40:41], s[88:89], 2
	s_add_u32 s40, s79, s40
	s_addc_u32 s41, s84, s41
	s_waitcnt lgkmcnt(4)
	v_mfma_f32_16x16x32_bf16 v[26:29], v[18:21], v[26:29], 0
	global_load_dwordx4 v[18:21], v82, s[40:41] nt
	s_lshl_b32 s96, s78, 2
	v_lshl_add_u64 v[64:65], s[40:41], 0, v[82:83]
	s_waitcnt lgkmcnt(2)
	v_mfma_f32_16x16x32_bf16 v[22:25], v[30:33], v[38:41], v[22:25]
	ds_read_b128 v[38:41], v103 offset:36992
	ds_read_b128 v[60:63], v164 offset:18624
	s_waitcnt lgkmcnt(3)
	v_mfma_f32_16x16x32_bf16 v[30:33], v[30:33], v[42:45], v[26:29]
	ds_read_b128 v[42:45], v103 offset:37056
	s_waitcnt lgkmcnt(2)
	v_mfma_f32_16x16x32_bf16 v[38:41], v[46:49], v[38:41], v[22:25]
	v_lshl_add_u64 v[26:27], v[64:65], 0, s[96:97]
	v_lshl_add_u64 v[64:65], v[26:27], 0, s[96:97]
	s_nop 0
	global_load_dwordx4 v[22:25], v[26:27], off nt
	s_nop 0
	global_load_dwordx4 v[26:29], v[64:65], off nt
	s_waitcnt lgkmcnt(0)
	v_mfma_f32_16x16x32_bf16 v[38:41], v[60:63], v[42:45], v[38:41]
	ds_read_b128 v[68:71], v103 offset:46208
	ds_read_b128 v[42:45], v103 offset:46272
	v_lshl_add_u64 v[64:65], v[64:65], 0, s[96:97]
	s_waitcnt lgkmcnt(1)
	v_mfma_f32_16x16x32_bf16 v[46:49], v[46:49], v[68:71], v[30:33]
	s_nop 2
	v_add_f32_e32 v38, v165, v38
	v_mul_f32_e32 v38, 0xbfb8aa3b, v38
	v_exp_f32_e32 v38, v38
	s_waitcnt lgkmcnt(0)
	v_mfma_f32_16x16x32_bf16 v[42:45], v[60:63], v[42:45], v[46:49]
	v_add_f32_e32 v39, v165, v39
	v_mul_f32_e32 v39, 0xbfb8aa3b, v39
	v_add_f32_e32 v30, 1.0, v38
	v_rcp_f32_e32 v38, v30
	v_exp_f32_e32 v39, v39
	global_load_dwordx4 v[30:33], v[64:65], off nt
	ds_read_u16 v47, v177 offset:18432
	ds_read_u16 v49, v177 offset:18720
	ds_read_u16 v59, v177 offset:19008
	ds_read_u16 v60, v177 offset:19296
	v_mul_f32_e64 v38, v38, -v168
	v_exp_f32_e32 v48, v38
	v_add_f32_e32 v38, v167, v42
	v_mul_f32_e32 v38, 0xbfb8aa3b, v38
	v_exp_f32_e32 v38, v38
	v_fma_f32 v42, -v48, v48, 1.0
	v_mul_f32_e32 v46, 0x4f800000, v42
	v_cmp_gt_f32_e32 vcc, s42, v42
	v_add_f32_e32 v38, 1.0, v38
	v_rcp_f32_e32 v38, v38
	v_cndmask_b32_e32 v42, v42, v46, vcc
	v_sqrt_f32_e32 v46, v42
	v_add_f32_e32 v39, 1.0, v39
	v_rcp_f32_e32 v39, v39
	v_add_f32_e32 v40, v165, v40
	v_add_u32_e32 v61, -1, v46
	v_fma_f32 v62, -v61, v46, v42
	v_cmp_ge_f32_e64 s[40:41], 0, v62
	v_add_u32_e32 v62, 1, v46
	v_mul_f32_e32 v40, 0xbfb8aa3b, v40
	v_cndmask_b32_e64 v61, v46, v61, s[40:41]
	v_fma_f32 v46, -v62, v46, v42
	v_cmp_lt_f32_e64 s[40:41], 0, v46
	v_exp_f32_e32 v40, v40
	v_add_f32_e32 v41, v165, v41
	v_cndmask_b32_e64 v46, v61, v62, s[40:41]
	v_mul_f32_e32 v61, 0x37800000, v46
	v_cndmask_b32_e32 v46, v46, v61, vcc
	v_cmp_class_f32_e32 vcc, v42, v158
	v_add_f32_e32 v40, 1.0, v40
	v_rcp_f32_e32 v40, v40
	v_cndmask_b32_e32 v42, v46, v42, vcc
	s_waitcnt lgkmcnt(3)
	v_lshlrev_b32_e32 v46, 16, v47
	v_mul_f32_e32 v38, v38, v46
	v_mul_f32_e32 v64, v38, v42
	v_mul_f32_e64 v38, v39, -v168
	v_exp_f32_e32 v39, v38
	v_add_f32_e32 v38, v167, v43
	v_mul_f32_e32 v38, 0xbfb8aa3b, v38
	v_exp_f32_e32 v38, v38
	v_fma_f32 v42, -v39, v39, 1.0
	v_mul_f32_e32 v43, 0x4f800000, v42
	v_cmp_gt_f32_e32 vcc, s42, v42
	v_add_f32_e32 v38, 1.0, v38
	v_rcp_f32_e32 v38, v38
	v_cndmask_b32_e32 v42, v42, v43, vcc
	v_sqrt_f32_e32 v43, v42
	v_mul_f32_e64 v40, v40, -v168
	v_exp_f32_e32 v65, v40
	v_add_f32_e32 v40, v167, v44
	v_add_u32_e32 v47, -1, v43
	v_fma_f32 v61, -v47, v43, v42
	v_cmp_ge_f32_e64 s[40:41], 0, v61
	v_add_u32_e32 v61, 1, v43
	v_fma_f32 v46, 0, v48, v64
	v_cndmask_b32_e64 v47, v43, v47, s[40:41]
	v_fma_f32 v43, -v61, v43, v42
	v_cmp_lt_f32_e64 s[40:41], 0, v43
	v_mul_f32_e32 v40, 0xbfb8aa3b, v40
	v_exp_f32_e32 v40, v40
	v_cndmask_b32_e64 v43, v47, v61, s[40:41]
	v_mul_f32_e32 v47, 0x37800000, v43
	v_cndmask_b32_e32 v43, v43, v47, vcc
	v_cmp_class_f32_e32 vcc, v42, v158
	v_mul_f32_e32 v41, 0xbfb8aa3b, v41
	v_exp_f32_e32 v41, v41
	v_cndmask_b32_e32 v42, v43, v42, vcc
	s_waitcnt lgkmcnt(2)
; #define LAS __attribute__((address_space(3)))
; DI float bf2f(unsigned h) { return __uint_as_float(h << 16); }
; DI unsigned pk2(float lo, float hi) { f32x2 v = {lo, hi}; bf16v2 b = __builtin_convertvector(v, bf16v2); return __builtin_bit_cast(unsigned, b); }
; DI float fsilu(float x) { return x * fsigmoid(x); }
; #define LDS_BAR() do { asm volatile("s_waitcnt lgkmcnt(0)" ::: "memory"); __builtin_amdgcn_s_barrier(); asm volatile("" ::: "memory"); } while (0)
; DI void rglru_scan_unit(Frame& F, const Mix0Args& a, int u) {
;     ...
;         const int sgi = ltile * 4 + fq;
;         SEGA[jj * 20 + sgi] = Aseg; SEGH[jj * 20 + sgi] = Hseg;
;         LDS_BAR();
;         float carry = HPREV[jj * 20 + (n & 1)]; float sa[15], sh[15];
;         { f32x4 a4[4], h4[4];
; #pragma unroll
;           for (int i = 0; i < 4; ++i) { a4[i] = *(const LAS f32x4*)(SEGA + jj * 20 + 4 * i); h4[i] = *(const LAS f32x4*)(SEGH + jj * 20 + 4 * i); }
; #pragma unroll
;           for (int s = 0; s < 15; ++s) { sa[s] = a4[s >> 2][s & 3]; sh[s] = h4[s >> 2][s & 3]; } }
; #pragma unroll
;         for (int s = 0; s < 15; ++s) carry = (s < sgi) ? sa[s] * carry + sh[s] : carry;
; #pragma unroll
;         for (int r = 0; r < 4; ++r) { carry = av[r] * carry + uv[r];
;             const float o = carry * fsilu(bf2f(gb_cur[r]));
;             obcol[(row0 + l0_ + 4 * fq + r) * a.out_ld] = (bf16)(pk2(o, 0.f) & 0xffffu); }
;         if (sgi == 15) HPREV[jj * 20 + ((n + 1) & 1)] = carry;
	v_lshlrev_b32_e32 v43, 16, v49
	v_mul_f32_e32 v38, v38, v43
	v_mul_f32_e32 v49, v38, v42
	v_fma_f32 v42, -v65, v65, 1.0
	v_mul_f32_e32 v43, 0x4f800000, v42
	v_cmp_gt_f32_e32 vcc, s42, v42
	v_fma_f32 v38, v39, v46, v49
	v_add_f32_e32 v40, 1.0, v40
	v_cndmask_b32_e32 v42, v42, v43, vcc
	v_sqrt_f32_e32 v43, v42
	v_rcp_f32_e32 v40, v40
	v_add_f32_e32 v41, 1.0, v41
	v_rcp_f32_e32 v41, v41
	v_add_u32_e32 v46, -1, v43
	v_fma_f32 v47, -v46, v43, v42
	v_cmp_ge_f32_e64 s[40:41], 0, v47
	v_add_u32_e32 v47, 1, v43
	v_mul_f32_e32 v44, v48, v39
	v_cndmask_b32_e64 v46, v43, v46, s[40:41]
	v_fma_f32 v43, -v47, v43, v42
	v_cmp_lt_f32_e64 s[40:41], 0, v43
	s_nop 1
	v_cndmask_b32_e64 v43, v46, v47, s[40:41]
	v_mul_f32_e32 v46, 0x37800000, v43
	v_cndmask_b32_e32 v43, v43, v46, vcc
	v_cmp_class_f32_e32 vcc, v42, v158
	s_nop 1
	v_cndmask_b32_e32 v42, v43, v42, vcc
	s_waitcnt lgkmcnt(1)
	v_lshlrev_b32_e32 v43, 16, v59
	v_mul_f32_e32 v40, v40, v43
	v_mul_f32_e32 v59, v40, v42
	v_fma_f32 v40, v65, v38, v59
	v_mul_f32_e64 v38, v41, -v168
	v_exp_f32_e32 v80, v38
	v_add_f32_e32 v38, v167, v45
	v_mul_f32_e32 v38, 0xbfb8aa3b, v38
	v_exp_f32_e32 v38, v38
	v_fma_f32 v41, -v80, v80, 1.0
	v_mul_f32_e32 v42, 0x4f800000, v41
	v_cmp_gt_f32_e32 vcc, s42, v41
	v_mul_f32_e32 v43, v65, v44
	v_add_f32_e32 v38, 1.0, v38
	v_cndmask_b32_e32 v41, v41, v42, vcc
	v_sqrt_f32_e32 v42, v41
	v_rcp_f32_e32 v38, v38
	v_add_u32_e32 v44, -1, v42
	v_fma_f32 v45, -v44, v42, v41
	v_cmp_ge_f32_e64 s[40:41], 0, v45
	v_add_u32_e32 v45, 1, v42
	s_nop 0
	v_cndmask_b32_e64 v44, v42, v44, s[40:41]
	v_fma_f32 v42, -v45, v42, v41
	v_cmp_lt_f32_e64 s[40:41], 0, v42
	s_nop 1
	v_cndmask_b32_e64 v42, v44, v45, s[40:41]
	v_mul_f32_e32 v44, 0x37800000, v42
	v_cndmask_b32_e32 v42, v42, v44, vcc
	v_cmp_class_f32_e32 vcc, v41, v158
	s_mov_b32 s40, 0x25600000
	s_nop 0
	v_cndmask_b32_e32 v41, v42, v41, vcc
	s_waitcnt lgkmcnt(0)
	v_lshlrev_b32_e32 v42, 16, v60
	v_mul_f32_e32 v38, v38, v42
	v_mul_f32_e32 v38, v38, v41
	v_fma_f32 v40, v80, v40, v38
	v_mul_f32_e32 v41, v80, v43
	ds_write2st64_b32 v150, v41, v40 offset0:236 offset1:246
	s_waitcnt lgkmcnt(0)
	s_barrier
	ds_read_b32 v81, v149 offset:55364
	ds_read_b128 v[40:43], v149 offset:60416
	ds_read_b128 v[44:47], v149 offset:62976
	ds_read_b128 v[60:63], v149 offset:60432
	ds_read_b128 v[68:71], v149 offset:60448
	ds_read_b128 v[72:75], v149 offset:62992
	ds_read_b128 v[76:79], v149 offset:63008
	ds_read_b128 v[178:181], v149 offset:60464
	ds_read_b128 v[184:187], v149 offset:63024
	s_waitcnt lgkmcnt(6)
	v_fma_f32 v40, v81, v40, v44
	v_cndmask_b32_e64 v40, v40, v81, s[10:11]
	v_fma_f32 v41, v41, v40, v45
	v_cndmask_b32_e64 v40, v40, v41, s[12:13]
	v_fma_f32 v41, v42, v40, v46
	v_cndmask_b32_e64 v40, v40, v41, s[14:15]
	v_fmac_f32_e32 v47, v43, v40
	v_cndmask_b32_e64 v40, v47, v40, s[0:1]
	s_waitcnt lgkmcnt(3)
	v_fma_f32 v41, v60, v40, v72
	v_cndmask_b32_e64 v40, v40, v41, s[16:17]
	v_fma_f32 v41, v61, v40, v73
	v_cndmask_b32_e64 v40, v40, v41, s[18:19]
	v_fma_f32 v41, v62, v40, v74
	v_cndmask_b32_e64 v40, v40, v41, s[20:21]
	v_fmac_f32_e32 v75, v63, v40
	v_cndmask_b32_e64 v40, v40, v75, s[38:39]
	s_waitcnt lgkmcnt(2)
	v_fma_f32 v41, v68, v40, v76
	v_cndmask_b32_e64 v40, v40, v41, s[22:23]
	v_fma_f32 v41, v69, v40, v77
	v_cndmask_b32_e64 v40, v40, v41, s[24:25]
	v_fma_f32 v41, v70, v40, v78
	v_cndmask_b32_e64 v40, v40, v41, s[26:27]
	v_fmac_f32_e32 v79, v71, v40
	v_mul_f32_e32 v42, 0xbfb8aa3b, v37
	v_cndmask_b32_e64 v40, v40, v79, s[4:5]
	v_exp_f32_e32 v42, v42
	s_waitcnt lgkmcnt(0)
	v_fma_f32 v41, v178, v40, v184
	v_cndmask_b32_e64 v40, v40, v41, s[28:29]
	v_fma_f32 v41, v179, v40, v185
	v_cndmask_b32_e64 v40, v40, v41, s[30:31]
	v_add_f32_e32 v41, 1.0, v42
	v_rcp_f32_e32 v41, v41
	v_fmac_f32_e32 v186, v180, v40
	v_cndmask_b32_e64 v40, v40, v186, s[34:35]
	v_fmac_f32_e32 v64, v48, v40
	v_mul_f32_e32 v37, v41, v37
	v_lshlrev_b32_e32 v41, 16, v36
	v_mul_f32_e32 v36, 0xbfb8aa3b, v41
	v_exp_f32_e32 v42, v36
	v_mul_f32_e32 v37, v37, v64
	v_add_co_u32_e32 v36, vcc, s40, v66
	v_cvt_pk_bf16_f32 v40, v37, s0
	s_nop 0
	v_addc_co_u32_e32 v37, vcc, 0, v67, vcc
	global_store_short v[36:37], v40, off
	v_add_f32_e32 v36, 1.0, v42
	v_rcp_f32_e32 v36, v36
	v_mul_f32_e32 v37, 0xbfb8aa3b, v34
	v_exp_f32_e32 v37, v37
	v_fmac_f32_e32 v49, v39, v64
	v_mul_f32_e32 v36, v36, v41
	v_mul_f32_e32 v36, v36, v49
	v_cvt_pk_bf16_f32 v39, v36, s0
	v_add_f32_e32 v36, 1.0, v37
	s_mov_b32 s40, 0x2560c000
	v_rcp_f32_e32 v40, v36
	v_add_co_u32_e32 v36, vcc, s40, v66
	v_fmac_f32_e32 v59, v65, v49
	s_nop 0
	v_addc_co_u32_e32 v37, vcc, 0, v67, vcc
	global_store_short v[36:37], v39, off
	s_waitcnt vmcnt(29)
	v_lshlrev_b32_e32 v36, 16, v35
	v_mul_f32_e32 v35, 0xbfb8aa3b, v36
	v_exp_f32_e32 v35, v35
	v_mul_f32_e32 v34, v40, v34
	v_mul_f32_e32 v34, v34, v59
	s_mov_b32 s40, 0x25618000
	v_add_f32_e32 v35, 1.0, v35
	v_rcp_f32_e32 v39, v35
	v_cvt_pk_bf16_f32 v37, v34, s0
	v_add_co_u32_e32 v34, vcc, s40, v66
	v_fmac_f32_e32 v38, v80, v59
	s_nop 0
	v_addc_co_u32_e32 v35, vcc, 0, v67, vcc
	global_store_short v[34:35], v37, off
	v_mul_f32_e32 v34, v39, v36
	v_mul_f32_e32 v34, v34, v38
	v_cvt_pk_bf16_f32 v36, v34, s0
	s_mov_b64 s[100:101], 0x25624000
	v_lshl_add_u64 v[34:35], v[66:67], 0, s[100:101]
	global_store_short v[34:35], v36, off
	s_and_saveexec_b64 s[40:41], s[34:35]
	ds_write_b32 v149, v38 offset:55360
	s_or_b64 exec, exec, s[40:41]
	s_waitcnt vmcnt(22)
; #define LAS __attribute__((address_space(3)))
; #define LDS_BAR() do { asm volatile("s_waitcnt lgkmcnt(0)" ::: "memory"); __builtin_amdgcn_s_barrier(); asm volatile("" ::: "memory"); } while (0)
; #define RG_LOAD(n_) do { const long r0_ = (long)rowbase + (long)(n_) * 64; \
;         _Pragma("unroll") for (int i = 0; i < 11; ++i) xr[i] = ((n_) == 0 && 8 * rg - 3 + i < 0) ? 0u : *(const unsigned*)(xcol + (size_t)(r0_ + 8 * rg - 3 + i) * N1); } while (0)
; #define RG_LOADG(n_) do { const long r0_ = (long)rowbase + (long)(n_) * 64; \
;         _Pragma("unroll") for (int i = 0; i < 4; ++i) gbr[i] = *(const unsigned short*)(gbcol + (size_t)(r0_ + l0_ + 4 * fq + i) * N1); } while (0)
; DI void rglru_scan_unit(Frame& F, const Mix0Args& a, int u) {
;     ...
;     RG_LOAD(0);
;     RG_STAGE(XC0);
;     unsigned gb_cur[4];
;     RG_LOAD(1); RG_LOADG(0);
;     LDS_BAR();
;     const int nsl = cv_on ? min(NCH / 4, max(0, (CV_NIT - 8 * F.vcu + NGW - 1) / NGW)) : 0;
;     auto rg_step = [&](int n, auto cvt) __attribute__((always_inline)) {
;         constexpr int CQ = decltype(cvt)::value; constexpr bool CV = CQ >= 0;
;         const size_t row0 = rowbase + (size_t)n * 64;
;         LAS uchar* XCc = XC0 + (n & 1) * 64 * S128; LAS uchar* XCn = XC0 + ((n + 1) & 1) * 64 * S128;
;         LAS float* SEGA = SEG0 + (n & 1) * 1280; LAS float* SEGH = SEGA + 640;
; #pragma unroll
;         for (int i = 0; i < 4; ++i) gb_cur[i] = gbr[i];
;         if (n + 1 < NCH) RG_STAGE(XCn);
;         if constexpr (CQ == 0) { if (n > 0) { const int ip = ((n >> 2) - 1) * NGW + gw; if (ip < CV_NIT) cv_finish(a.cv, ip, lane, cq0, cq1, cq2, cq3, CVS); } }
;         if (n + 2 < NCH) RG_LOAD(n + 2);
;         if (n + 1 < NCH) RG_LOADG(n + 1);
;         if constexpr (CV) { int idx = (n >> 2) * NGW + gw; idx = idx < CV_NIT ? idx : idx - CV_NIT;
;             if constexpr (CQ == 0) cv_issue_q(a.cv, idx, lane, cq0, 0); else if constexpr (CQ == 1) cv_issue_q(a.cv, idx, lane, cq1, 4); else if constexpr (CQ == 2) cv_issue_q(a.cv, idx, lane, cq2, 8); else cv_issue_q(a.cv, idx, lane, cq3, 12); }
	v_lshlrev_b32_e32 v34, 16, v130
	v_and_b32_e32 v35, 0xffff0000, v130
	v_pk_fma_f32 v[34:35], v[104:105], v[34:35], v[100:101]
	s_waitcnt vmcnt(21)
	v_lshlrev_b32_e32 v36, 16, v132
	v_and_b32_e32 v37, 0xffff0000, v132
	v_pk_fma_f32 v[34:35], v[106:107], v[36:37], v[34:35]
	s_waitcnt vmcnt(20)
	v_lshlrev_b32_e32 v38, 16, v134
	v_and_b32_e32 v39, 0xffff0000, v134
	v_pk_fma_f32 v[34:35], v[108:109], v[38:39], v[34:35]
	s_waitcnt vmcnt(19)
	v_lshlrev_b32_e32 v40, 16, v169
	v_and_b32_e32 v41, 0xffff0000, v169
	v_pk_fma_f32 v[34:35], v[110:111], v[40:41], v[34:35]
	s_or_b32 s40, s93, 2
	v_cvt_pk_bf16_f32 v42, v34, v35
	v_pk_fma_f32 v[34:35], v[104:105], v[36:37], v[100:101]
	s_waitcnt vmcnt(18)
	v_lshlrev_b32_e32 v36, 16, v170
	v_pk_fma_f32 v[34:35], v[106:107], v[38:39], v[34:35]
	v_and_b32_e32 v37, 0xffff0000, v170
	v_pk_fma_f32 v[34:35], v[108:109], v[40:41], v[34:35]
	s_cmpk_gt_u32 s40, 0x7d
	v_pk_fma_f32 v[34:35], v[110:111], v[36:37], v[34:35]
	s_nop 0
	v_cvt_pk_bf16_f32 v34, v34, v35
	ds_write2_b32 v183, v42, v34 offset1:72
	v_pk_fma_f32 v[34:35], v[104:105], v[38:39], v[100:101]
	s_waitcnt vmcnt(17)
	v_lshlrev_b32_e32 v38, 16, v171
	v_pk_fma_f32 v[34:35], v[106:107], v[40:41], v[34:35]
	v_and_b32_e32 v39, 0xffff0000, v171
	v_pk_fma_f32 v[34:35], v[108:109], v[36:37], v[34:35]
	s_nop 0
	v_pk_fma_f32 v[34:35], v[110:111], v[38:39], v[34:35]
	s_nop 0
	v_cvt_pk_bf16_f32 v42, v34, v35
	v_pk_fma_f32 v[34:35], v[104:105], v[40:41], v[100:101]
	s_waitcnt vmcnt(16)
	v_lshlrev_b32_e32 v40, 16, v172
	v_pk_fma_f32 v[34:35], v[106:107], v[36:37], v[34:35]
	v_and_b32_e32 v41, 0xffff0000, v172
	v_pk_fma_f32 v[34:35], v[108:109], v[38:39], v[34:35]
	s_nop 0
	v_pk_fma_f32 v[34:35], v[110:111], v[40:41], v[34:35]
	s_nop 0
	v_cvt_pk_bf16_f32 v34, v34, v35
	ds_write2_b32 v183, v42, v34 offset0:144 offset1:216
	v_pk_fma_f32 v[34:35], v[104:105], v[36:37], v[100:101]
	s_waitcnt vmcnt(15)
	v_lshlrev_b32_e32 v36, 16, v173
	v_pk_fma_f32 v[34:35], v[106:107], v[38:39], v[34:35]
	v_and_b32_e32 v37, 0xffff0000, v173
	v_pk_fma_f32 v[34:35], v[108:109], v[40:41], v[34:35]
	s_nop 0
	v_pk_fma_f32 v[34:35], v[110:111], v[36:37], v[34:35]
	s_nop 0
	v_cvt_pk_bf16_f32 v42, v34, v35
	v_pk_fma_f32 v[34:35], v[104:105], v[38:39], v[100:101]
	s_waitcnt vmcnt(14)
	v_lshlrev_b32_e32 v38, 16, v174
	v_pk_fma_f32 v[34:35], v[106:107], v[40:41], v[34:35]
	v_and_b32_e32 v39, 0xffff0000, v174
	v_pk_fma_f32 v[34:35], v[108:109], v[36:37], v[34:35]
	s_nop 0
	v_pk_fma_f32 v[34:35], v[110:111], v[38:39], v[34:35]
	s_nop 0
	v_cvt_pk_bf16_f32 v34, v34, v35
	ds_write2_b32 v182, v42, v34 offset0:32 offset1:104
	v_pk_fma_f32 v[34:35], v[104:105], v[40:41], v[100:101]
	s_waitcnt vmcnt(13)
	v_lshlrev_b32_e32 v40, 16, v175
	v_pk_fma_f32 v[34:35], v[106:107], v[36:37], v[34:35]
	v_and_b32_e32 v41, 0xffff0000, v175
	v_pk_fma_f32 v[34:35], v[108:109], v[38:39], v[34:35]
	s_nop 0
	v_pk_fma_f32 v[34:35], v[110:111], v[40:41], v[34:35]
	s_nop 0
	v_cvt_pk_bf16_f32 v42, v34, v35
	v_pk_fma_f32 v[34:35], v[104:105], v[36:37], v[100:101]
	s_waitcnt vmcnt(12)
	v_lshlrev_b32_e32 v36, 16, v176
	v_pk_fma_f32 v[34:35], v[106:107], v[38:39], v[34:35]
	v_and_b32_e32 v37, 0xffff0000, v176
	v_pk_fma_f32 v[34:35], v[108:109], v[40:41], v[34:35]
	s_nop 0
	v_pk_fma_f32 v[34:35], v[110:111], v[36:37], v[34:35]
	s_nop 0
	v_cvt_pk_bf16_f32 v34, v34, v35
	ds_write2_b32 v182, v42, v34 offset0:176 offset1:248
	s_cbranch_scc1 .LBB0_281
	s_mov_b64 s[100:101], 0x25ee4000
	v_lshl_add_u64 v[34:35], v[50:51], 0, s[100:101]
	global_load_dword v130, v[34:35], off
	s_mov_b64 s[100:101], 0x25ef0000
	v_lshl_add_u64 v[34:35], v[50:51], 0, s[100:101]
	global_load_dword v132, v[34:35], off
	s_mov_b64 s[100:101], 0x25efc000
	v_lshl_add_u64 v[34:35], v[50:51], 0, s[100:101]
	global_load_dword v134, v[34:35], off
	s_mov_b64 s[100:101], 0x25f08000
	v_lshl_add_u64 v[34:35], v[50:51], 0, s[100:101]
	global_load_dword v169, v[34:35], off
	s_mov_b64 s[100:101], 0x25f14000
	v_lshl_add_u64 v[34:35], v[50:51], 0, s[100:101]
	global_load_dword v170, v[34:35], off
	s_mov_b64 s[100:101], 0x25f20000
	v_lshl_add_u64 v[34:35], v[50:51], 0, s[100:101]
	global_load_dword v171, v[34:35], off
	s_mov_b64 s[100:101], 0x25f2c000
	v_lshl_add_u64 v[34:35], v[50:51], 0, s[100:101]
	global_load_dword v172, v[34:35], off
	s_mov_b64 s[100:101], 0x25f38000
	v_lshl_add_u64 v[34:35], v[50:51], 0, s[100:101]
	global_load_dword v173, v[34:35], off
	s_mov_b64 s[100:101], 0x25f44000
	v_lshl_add_u64 v[34:35], v[50:51], 0, s[100:101]
	global_load_dword v174, v[34:35], off
	s_mov_b64 s[100:101], 0x25f50000
	v_lshl_add_u64 v[34:35], v[50:51], 0, s[100:101]
	global_load_dword v175, v[34:35], off
	s_mov_b64 s[100:101], 0x25f5c000
	v_lshl_add_u64 v[34:35], v[50:51], 0, s[100:101]
	global_load_dword v176, v[34:35], off

; #define LAS __attribute__((address_space(3)))
; DI float bf2f(unsigned h) { return __uint_as_float(h << 16); }
; DI void cv_issue_q(const CvJob& j, int idx, int lane, f32x4 (&v)[4], int r0) {
;     const float* W; int K, N, item; bf16* WT; const float* ks; cv_decode(j, idx, W, K, N, WT, ks, item);
;     const int nblk = N / 64, kb = item / nblk, nb = item % nblk, k0 = 64 * kb, n0 = 64 * nb, q = lane >> 4, c16 = lane & 15;
;     const char* ub = (const char*)(W + (size_t)(k0 + r0) * N + n0);
;     const unsigned vo = (unsigned)((16 * q) * N + 4 * c16) * 4u;
; #pragma unroll
;     for (int i = 0; i < 4; ++i) v[i] = *(const f32x4*)(ub + (size_t)i * N * 4 + vo);
; }
; DI void rglru_scan_unit(Frame& F, const Mix0Args& a, int u) {
;     ...
;         if constexpr (CV) { int idx = (n >> 2) * NGW + gw; idx = idx < CV_NIT ? idx : idx - CV_NIT;
;             if constexpr (CQ == 0) cv_issue_q(a.cv, idx, lane, cq0, 0); else if constexpr (CQ == 1) cv_issue_q(a.cv, idx, lane, cq1, 4); else if constexpr (CQ == 2) cv_issue_q(a.cv, idx, lane, cq2, 8); else cv_issue_q(a.cv, idx, lane, cq3, 12); }
;         const f32x4 zero4 = (f32x4){0.f, 0.f, 0.f, 0.f};
;         float av[4], uv[4]; float Aseg = 1.f, Hseg = 0.f;
;         { bf16x8 xf[4], waf[4], wxf[4]; unsigned xcr[4];
; #pragma unroll
;           for (int ks = 0; ks < 4; ++ks) { xf[ks] = *(const LAS bf16x8*)(XCc + (l0_ + fr) * S128 + ks * 64 + fq * 16);
;               waf[ks] = *(const LAS bf16x8*)(WAT + (16 * jtile + fr) * S128 + ks * 64 + fq * 16); wxf[ks] = *(const LAS bf16x8*)(WXT + (16 * jtile + fr) * S128 + ks * 64 + fq * 16); }
; #pragma unroll
;           for (int r = 0; r < 4; ++r) xcr[r] = *(const LAS unsigned short*)(XCc + (l0_ + 4 * fq + r) * S128 + (qq * 32 + jj) * 2);
;           f32x4 R = zero4, I = zero4;
; #pragma unroll
;           for (int ks = 0; ks < 4; ++ks) { R = __builtin_amdgcn_mfma_f32_16x16x32_bf16(xf[ks], waf[ks], R, 0, 0, 0); I = __builtin_amdgcn_mfma_f32_16x16x32_bf16(xf[ks], wxf[ks], I, 0, 0, 0); }
; #pragma unroll
;           for (int r = 0; r < 4; ++r) {
;               const float rr = fsigmoid(R[r] + bav), ig = fsigmoid(I[r] + bxv);
;               const float aa = fexp2(-sp8l2 * rr); const float om = __builtin_fmaf(-aa, aa, 1.0f);
;               av[r] = aa; uv[r] = __builtin_sqrtf(om) * (ig * bf2f(xcr[r]));
;               Hseg = aa * Hseg + uv[r]; Aseg *= aa; } }
.LBB0_287:
	s_lshr_b32 s79, s78, 6
	v_cvt_f32_u32_e32 v34, s79
	s_sub_i32 s90, 0, s79
	s_abs_i32 s89, s84
	s_ashr_i32 s88, s84, 31
	v_rcp_iflag_f32_e32 v34, v34
	v_mul_u32_u24_e32 v63, s78, v102
	v_or_b32_e32 v63, v63, v125
	v_lshlrev_b32_e32 v82, 2, v63
	v_mul_f32_e32 v34, 0x4f7ffffe, v34
	v_cvt_u32_f32_e32 v34, v34
	s_waitcnt vmcnt(15)
	v_lshlrev_b32_e32 v58, 16, v58
	s_waitcnt vmcnt(14)
	v_lshlrev_b32_e32 v56, 16, v56
	s_waitcnt vmcnt(13)
	v_lshlrev_b32_e32 v55, 16, v55
	v_readfirstlane_b32 s91, v34
	ds_read_b128 v[34:37], v164
	ds_read_b128 v[38:41], v103 offset:36864
	s_mul_i32 s90, s90, s91
	s_mul_hi_u32 s90, s91, s90
	s_add_i32 s91, s91, s90
	s_mul_hi_u32 s90, s89, s91
	s_mul_i32 s91, s90, s79
	s_sub_i32 s89, s89, s91
	s_add_i32 vcc_lo, s90, 1
	s_sub_i32 s91, s89, s79
	s_cmp_ge_u32 s89, s79
	ds_read_b128 v[42:45], v103 offset:46080
	ds_read_b128 v[46:49], v164 offset:64
	ds_read_b128 v[68:71], v103 offset:36928
	ds_read_b128 v[72:75], v103 offset:46144
	ds_read_b128 v[76:79], v164 offset:128
	s_cselect_b32 s90, vcc_lo, s90
	s_waitcnt lgkmcnt(5)
	v_mfma_f32_16x16x32_bf16 v[38:41], v[34:37], v[38:41], 0
	s_cselect_b32 s89, s91, s89
	s_add_i32 s91, s90, 1
	s_cmp_ge_u32 s89, s79
	s_cselect_b32 s89, s91, s90
	s_waitcnt lgkmcnt(4)
	v_mfma_f32_16x16x32_bf16 v[34:37], v[34:37], v[42:45], 0
	s_xor_b32 s89, s89, s88
	s_sub_i32 s88, s89, s88
	s_mul_i32 s79, s88, s79
	s_waitcnt lgkmcnt(2)
	v_mfma_f32_16x16x32_bf16 v[38:41], v[46:49], v[68:71], v[38:41]
	ds_read_b128 v[42:45], v103 offset:36992
	ds_read_b128 v[68:71], v164 offset:192
	s_lshl_b32 s88, s88, 6
	s_sub_i32 s79, s84, s79
	s_or_b32 s84, s88, 8
	s_waitcnt lgkmcnt(3)
	v_mfma_f32_16x16x32_bf16 v[34:37], v[46:49], v[72:75], v[34:37]
	ds_read_b128 v[46:49], v103 offset:37056
	s_mul_hi_i32 s91, s84, s78
	s_mul_i32 s90, s84, s78
	s_waitcnt lgkmcnt(2)
	v_mfma_f32_16x16x32_bf16 v[72:75], v[76:79], v[42:45], v[38:41]
	s_lshl_b32 s88, s79, 6
	s_lshl_b64 s[90:91], s[90:91], 2
	s_add_u32 s79, s40, s90
	s_addc_u32 s84, s41, s91
	s_ashr_i32 s89, s88, 31
	s_lshl_b64 s[40:41], s[88:89], 2
	s_waitcnt lgkmcnt(0)
	v_mfma_f32_16x16x32_bf16 v[72:75], v[68:71], v[46:49], v[72:75]
	s_add_u32 s40, s79, s40
	s_addc_u32 s41, s84, s41
	s_lshl_b32 s96, s78, 2
	v_lshl_add_u64 v[64:65], s[40:41], 0, v[82:83]
	v_lshl_add_u64 v[64:65], v[64:65], 0, s[96:97]
	s_nop 2
	v_add_f32_e32 v46, v165, v72
	v_lshl_add_u64 v[80:81], v[64:65], 0, s[96:97]
	global_load_dwordx4 v[38:41], v[64:65], off nt
	global_load_dwordx4 v[42:45], v[80:81], off nt
	ds_read_b128 v[178:181], v103 offset:46208
	ds_read_b128 v[182:185], v103 offset:46272
	v_mul_f32_e32 v46, 0xbfb8aa3b, v46
	v_exp_f32_e32 v48, v46
	s_waitcnt lgkmcnt(1)
	v_mfma_f32_16x16x32_bf16 v[76:79], v[76:79], v[178:181], v[34:37]
	v_lshl_add_u64 v[46:47], v[80:81], 0, s[96:97]
	v_add_f32_e32 v73, v165, v73
	s_nop 0
	v_add_f32_e32 v34, 1.0, v48
	v_rcp_f32_e32 v63, v34
	s_waitcnt lgkmcnt(0)
	v_mfma_f32_16x16x32_bf16 v[68:71], v[68:71], v[182:185], v[76:79]
	global_load_dwordx4 v[34:37], v82, s[40:41] nt
	s_nop 0
	global_load_dwordx4 v[46:49], v[46:47], off nt
	v_mul_f32_e32 v73, 0xbfb8aa3b, v73
	v_mul_f32_e64 v63, v63, -v168
	v_exp_f32_e32 v64, v63
	s_nop 1
	v_add_f32_e32 v63, v167, v68
	v_mul_f32_e32 v63, 0xbfb8aa3b, v63
	v_exp_f32_e32 v63, v63
	v_fma_f32 v65, -v64, v64, 1.0
	v_mul_f32_e32 v68, 0x4f800000, v65
	v_cmp_gt_f32_e32 vcc, s42, v65
	v_exp_f32_e32 v73, v73
	v_add_f32_e32 v63, 1.0, v63
	v_cndmask_b32_e32 v65, v65, v68, vcc
	v_sqrt_f32_e32 v68, v65
	v_rcp_f32_e32 v63, v63
	ds_read_u16 v72, v113
	ds_read_u16 v76, v113 offset:288
	ds_read_u16 v77, v113 offset:576
	ds_read_u16 v78, v113 offset:864
	v_add_u32_e32 v79, -1, v68
	v_fma_f32 v80, -v79, v68, v65
	v_cmp_ge_f32_e64 s[40:41], 0, v80
	v_add_u32_e32 v80, 1, v68
	s_waitcnt lgkmcnt(3)
	v_lshlrev_b32_e32 v72, 16, v72
	v_cndmask_b32_e64 v79, v68, v79, s[40:41]
	v_fma_f32 v68, -v80, v68, v65
	v_cmp_lt_f32_e64 s[40:41], 0, v68
	v_mul_f32_e32 v63, v63, v72
	s_nop 0
	v_cndmask_b32_e64 v68, v79, v80, s[40:41]
	v_mul_f32_e32 v79, 0x37800000, v68
	v_cndmask_b32_e32 v68, v68, v79, vcc
	v_cmp_class_f32_e32 vcc, v65, v158
	s_nop 1
	v_cndmask_b32_e32 v65, v68, v65, vcc
	v_add_f32_e32 v68, 1.0, v73
	v_rcp_f32_e32 v68, v68
	v_mul_f32_e32 v80, v63, v65
	v_mul_f32_e64 v63, v68, -v168
	v_exp_f32_e32 v81, v63
	v_add_f32_e32 v63, v167, v69
	v_mul_f32_e32 v63, 0xbfb8aa3b, v63
	v_exp_f32_e32 v63, v63
	v_fma_f32 v65, -v81, v81, 1.0
	v_mul_f32_e32 v68, 0x4f800000, v65
	v_cmp_gt_f32_e32 vcc, s42, v65
	v_add_f32_e32 v63, 1.0, v63
	v_rcp_f32_e32 v63, v63
	v_cndmask_b32_e32 v65, v65, v68, vcc
	v_sqrt_f32_e32 v68, v65
	v_fma_f32 v69, 0, v64, v80
	v_add_u32_e32 v72, -1, v68
	v_fma_f32 v73, -v72, v68, v65
	v_cmp_ge_f32_e64 s[40:41], 0, v73
	v_add_u32_e32 v73, 1, v68
	s_nop 0
	v_cndmask_b32_e64 v72, v68, v72, s[40:41]
	v_fma_f32 v68, -v73, v68, v65
	v_cmp_lt_f32_e64 s[40:41], 0, v68
	s_nop 1
	v_cndmask_b32_e64 v68, v72, v73, s[40:41]
	v_mul_f32_e32 v72, 0x37800000, v68
	v_cndmask_b32_e32 v68, v68, v72, vcc
	v_add_f32_e32 v72, v165, v74
	v_mul_f32_e32 v72, 0xbfb8aa3b, v72
	v_exp_f32_e32 v72, v72
	v_cmp_class_f32_e32 vcc, v65, v158
	v_add_f32_e32 v72, 1.0, v72
	v_rcp_f32_e32 v72, v72
	v_cndmask_b32_e32 v65, v68, v65, vcc
	s_waitcnt lgkmcnt(2)
; #define LAS __attribute__((address_space(3)))
; DI float bf2f(unsigned h) { return __uint_as_float(h << 16); }
; DI unsigned pk2(float lo, float hi) { f32x2 v = {lo, hi}; bf16v2 b = __builtin_convertvector(v, bf16v2); return __builtin_bit_cast(unsigned, b); }
; DI float fsilu(float x) { return x * fsigmoid(x); }
; #define LDS_BAR() do { asm volatile("s_waitcnt lgkmcnt(0)" ::: "memory"); __builtin_amdgcn_s_barrier(); asm volatile("" ::: "memory"); } while (0)
; DI void rglru_scan_unit(Frame& F, const Mix0Args& a, int u) {
;     ...
;         const int sgi = ltile * 4 + fq;
;         SEGA[jj * 20 + sgi] = Aseg; SEGH[jj * 20 + sgi] = Hseg;
;         LDS_BAR();
;         float carry = HPREV[jj * 20 + (n & 1)]; float sa[15], sh[15];
;         { f32x4 a4[4], h4[4];
; #pragma unroll
;           for (int i = 0; i < 4; ++i) { a4[i] = *(const LAS f32x4*)(SEGA + jj * 20 + 4 * i); h4[i] = *(const LAS f32x4*)(SEGH + jj * 20 + 4 * i); }
; #pragma unroll
;           for (int s = 0; s < 15; ++s) { sa[s] = a4[s >> 2][s & 3]; sh[s] = h4[s >> 2][s & 3]; } }
; #pragma unroll
;         for (int s = 0; s < 15; ++s) carry = (s < sgi) ? sa[s] * carry + sh[s] : carry;
; #pragma unroll
;         for (int r = 0; r < 4; ++r) { carry = av[r] * carry + uv[r];
;             const float o = carry * fsilu(bf2f(gb_cur[r]));
;             obcol[(row0 + l0_ + 4 * fq + r) * a.out_ld] = (bf16)(pk2(o, 0.f) & 0xffffu); }
;         if (sgi == 15) HPREV[jj * 20 + ((n + 1) & 1)] = carry;
	v_lshlrev_b32_e32 v68, 16, v76
	v_mul_f32_e32 v63, v63, v68
	v_mul_f32_e32 v82, v63, v65
	v_mul_f32_e64 v65, v72, -v168
	v_exp_f32_e32 v122, v65
	v_fma_f32 v63, v81, v69, v82
	v_add_f32_e32 v65, v167, v70
	v_mul_f32_e32 v65, 0xbfb8aa3b, v65
	v_fma_f32 v68, -v122, v122, 1.0
	v_mul_f32_e32 v69, 0x4f800000, v68
	v_cmp_gt_f32_e32 vcc, s42, v68
	v_exp_f32_e32 v65, v65
	v_mul_f32_e32 v70, v64, v81
	v_cndmask_b32_e32 v68, v68, v69, vcc
	v_sqrt_f32_e32 v69, v68
	v_add_f32_e32 v65, 1.0, v65
	v_rcp_f32_e32 v65, v65
	v_mul_f32_e32 v70, v122, v70
	v_add_u32_e32 v72, -1, v69
	v_fma_f32 v73, -v72, v69, v68
	v_cmp_ge_f32_e64 s[40:41], 0, v73
	v_add_u32_e32 v73, 1, v69
	s_nop 0
	v_cndmask_b32_e64 v72, v69, v72, s[40:41]
	v_fma_f32 v69, -v73, v69, v68
	v_cmp_lt_f32_e64 s[40:41], 0, v69
	s_nop 1
	v_cndmask_b32_e64 v69, v72, v73, s[40:41]
	v_mul_f32_e32 v72, 0x37800000, v69
	v_cndmask_b32_e32 v69, v69, v72, vcc
	v_add_f32_e32 v72, v165, v75
	v_mul_f32_e32 v72, 0xbfb8aa3b, v72
	v_exp_f32_e32 v72, v72
	v_cmp_class_f32_e32 vcc, v68, v158
	v_add_f32_e32 v72, 1.0, v72
	v_rcp_f32_e32 v72, v72
	v_cndmask_b32_e32 v68, v69, v68, vcc
	s_waitcnt lgkmcnt(1)
	v_lshlrev_b32_e32 v69, 16, v77
	v_mul_f32_e32 v65, v65, v69
	v_mul_f32_e32 v124, v65, v68
	v_fma_f32 v65, v122, v63, v124
	v_mul_f32_e64 v63, v72, -v168
	v_exp_f32_e32 v126, v63
	v_add_f32_e32 v63, v167, v71
	v_mul_f32_e32 v63, 0xbfb8aa3b, v63
	v_exp_f32_e32 v63, v63
	v_fma_f32 v68, -v126, v126, 1.0
	v_mul_f32_e32 v69, 0x4f800000, v68
	v_cmp_gt_f32_e32 vcc, s42, v68
	v_add_f32_e32 v63, 1.0, v63
	v_rcp_f32_e32 v63, v63
	v_cndmask_b32_e32 v68, v68, v69, vcc
	v_sqrt_f32_e32 v69, v68
	s_nop 0
	v_add_u32_e32 v71, -1, v69
	v_fma_f32 v72, -v71, v69, v68
	v_cmp_ge_f32_e64 s[40:41], 0, v72
	v_add_u32_e32 v72, 1, v69
	s_nop 0
	v_cndmask_b32_e64 v71, v69, v71, s[40:41]
	v_fma_f32 v69, -v72, v69, v68
	v_cmp_lt_f32_e64 s[40:41], 0, v69
	s_nop 1
	v_cndmask_b32_e64 v69, v71, v72, s[40:41]
	v_mul_f32_e32 v71, 0x37800000, v69
	v_cndmask_b32_e32 v69, v69, v71, vcc
	v_cmp_class_f32_e32 vcc, v68, v158
	s_mov_b32 s40, 0x25900000
	s_nop 0
	v_cndmask_b32_e32 v68, v69, v68, vcc
	s_waitcnt lgkmcnt(0)
	v_lshlrev_b32_e32 v69, 16, v78
	v_mul_f32_e32 v63, v63, v69
	v_mul_f32_e32 v63, v63, v68
	v_fma_f32 v65, v126, v65, v63
	v_mul_f32_e32 v68, v126, v70
	ds_write2st64_b32 v150, v68, v65 offset0:216 offset1:226
	s_waitcnt lgkmcnt(0)
	s_barrier
	ds_read_b32 v65, v149 offset:55360
	ds_read_b128 v[68:71], v149 offset:57856
	ds_read_b128 v[72:75], v149 offset:57872
	ds_read_b128 v[76:79], v149 offset:57888
	ds_read_b128 v[178:181], v149 offset:55296
	ds_read_b128 v[182:185], v149 offset:55312
	ds_read_b128 v[186:189], v149 offset:55328
	ds_read_b128 v[190:193], v149 offset:55344
	ds_read_b128 v[194:197], v149 offset:57904
	s_waitcnt lgkmcnt(4)
	v_fma_f32 v68, v65, v178, v68
	v_cndmask_b32_e64 v65, v68, v65, s[10:11]
	v_fma_f32 v68, v179, v65, v69
	v_cndmask_b32_e64 v65, v65, v68, s[12:13]
	v_fma_f32 v68, v180, v65, v70
	v_cndmask_b32_e64 v65, v65, v68, s[14:15]
	v_fmac_f32_e32 v71, v181, v65
	v_cndmask_b32_e64 v65, v71, v65, s[0:1]
	s_waitcnt lgkmcnt(3)
	v_fma_f32 v68, v182, v65, v72
	v_cndmask_b32_e64 v65, v65, v68, s[16:17]
	v_fma_f32 v68, v183, v65, v73
	v_cndmask_b32_e64 v65, v65, v68, s[18:19]
	v_fma_f32 v68, v184, v65, v74
	v_cndmask_b32_e64 v65, v65, v68, s[20:21]
	v_fmac_f32_e32 v75, v185, v65
	v_cndmask_b32_e64 v65, v65, v75, s[38:39]
	s_waitcnt lgkmcnt(2)
	v_fma_f32 v68, v186, v65, v76
	v_cndmask_b32_e64 v65, v65, v68, s[22:23]
	v_fma_f32 v68, v187, v65, v77
	v_cndmask_b32_e64 v65, v65, v68, s[24:25]
	v_fma_f32 v68, v188, v65, v78
	v_cndmask_b32_e64 v65, v65, v68, s[26:27]
	v_fmac_f32_e32 v79, v189, v65
	v_mul_f32_e32 v69, 0xbfb8aa3b, v58
	v_cndmask_b32_e64 v65, v65, v79, s[4:5]
	v_exp_f32_e32 v69, v69
	s_waitcnt lgkmcnt(0)
	v_fma_f32 v68, v190, v65, v194
	v_cndmask_b32_e64 v65, v65, v68, s[28:29]
	v_fma_f32 v68, v191, v65, v195
	v_cndmask_b32_e64 v65, v65, v68, s[30:31]
	v_add_f32_e32 v68, 1.0, v69
	v_rcp_f32_e32 v68, v68
	v_fmac_f32_e32 v196, v192, v65
	v_cndmask_b32_e64 v65, v65, v196, s[34:35]
	v_fmac_f32_e32 v80, v64, v65
	v_mul_f32_e32 v64, 0xbfb8aa3b, v56
	v_mul_f32_e32 v58, v68, v58
	v_exp_f32_e32 v68, v64
	v_mul_f32_e32 v58, v58, v80
	v_add_co_u32_e32 v64, vcc, s40, v66
	v_cvt_pk_bf16_f32 v58, v58, s0
	s_nop 0
	v_addc_co_u32_e32 v65, vcc, 0, v67, vcc
	global_store_short v[64:65], v58, off
	v_add_f32_e32 v58, 1.0, v68
	v_mul_f32_e32 v64, 0xbfb8aa3b, v55
	v_rcp_f32_e32 v58, v58
	v_exp_f32_e32 v64, v64
	v_fmac_f32_e32 v82, v81, v80
	s_mov_b32 s40, 0x2590c000
	v_mul_f32_e32 v56, v58, v56
	v_add_f32_e32 v58, 1.0, v64
	v_rcp_f32_e32 v58, v58
	v_mul_f32_e32 v56, v56, v82
	v_add_co_u32_e32 v64, vcc, s40, v66
	v_cvt_pk_bf16_f32 v56, v56, s0
	s_nop 0
	v_addc_co_u32_e32 v65, vcc, 0, v67, vcc
	v_mul_f32_e32 v55, v58, v55
	s_waitcnt vmcnt(17)
	v_lshlrev_b32_e32 v58, 16, v57
	global_store_short v[64:65], v56, off
	v_mul_f32_e32 v56, 0xbfb8aa3b, v58
	v_exp_f32_e32 v57, v56
	v_fmac_f32_e32 v124, v122, v82
	s_mov_b32 s40, 0x25918000
	v_mul_f32_e32 v55, v55, v124
	v_add_f32_e32 v57, 1.0, v57
	v_rcp_f32_e32 v64, v57
	v_add_co_u32_e32 v56, vcc, s40, v66
	v_cvt_pk_bf16_f32 v55, v55, s0
	s_nop 0
	v_addc_co_u32_e32 v57, vcc, 0, v67, vcc
	global_store_short v[56:57], v55, off
	v_fmac_f32_e32 v63, v126, v124
	v_mul_f32_e32 v55, v64, v58
	v_mul_f32_e32 v55, v55, v63
	s_mov_b64 s[100:101], 0x25924000
	v_lshl_add_u64 v[56:57], v[66:67], 0, s[100:101]
	v_cvt_pk_bf16_f32 v55, v55, s0
	global_store_short v[56:57], v55, off
	s_and_saveexec_b64 s[40:41], s[34:35]
	ds_write_b32 v149, v63 offset:55364
	s_or_b64 exec, exec, s[40:41]
	s_or_b32 s78, s93, 3
	s_cmpk_lt_u32 s78, 0x7f
	s_cselect_b64 s[40:41], -1, 0
	s_cmpk_gt_u32 s78, 0x7e
	s_cbranch_scc1 .LBB0_291
	v_lshlrev_b32_e32 v56, 16, v130
	v_and_b32_e32 v57, 0xffff0000, v130
	v_pk_fma_f32 v[56:57], v[104:105], v[56:57], v[100:101]
	v_lshlrev_b32_e32 v64, 16, v132
	v_and_b32_e32 v65, 0xffff0000, v132
	v_pk_fma_f32 v[56:57], v[106:107], v[64:65], v[56:57]
	v_lshlrev_b32_e32 v68, 16, v134
	v_and_b32_e32 v69, 0xffff0000, v134
	v_pk_fma_f32 v[56:57], v[108:109], v[68:69], v[56:57]
	s_waitcnt vmcnt(19)
	v_lshlrev_b32_e32 v70, 16, v169
	v_and_b32_e32 v71, 0xffff0000, v169
	v_pk_fma_f32 v[56:57], v[110:111], v[70:71], v[56:57]
	s_nop 0
	v_cvt_pk_bf16_f32 v55, v56, v57
	v_pk_fma_f32 v[56:57], v[104:105], v[64:65], v[100:101]
	s_waitcnt vmcnt(18)
	v_lshlrev_b32_e32 v64, 16, v170
	v_pk_fma_f32 v[56:57], v[106:107], v[68:69], v[56:57]
	v_and_b32_e32 v65, 0xffff0000, v170
	v_pk_fma_f32 v[56:57], v[108:109], v[70:71], v[56:57]
	s_nop 0
	v_pk_fma_f32 v[56:57], v[110:111], v[64:65], v[56:57]
	s_nop 0
	v_cvt_pk_bf16_f32 v56, v56, v57
	ds_write2_b32 v123, v55, v56 offset1:72
	v_pk_fma_f32 v[56:57], v[104:105], v[68:69], v[100:101]
	s_waitcnt vmcnt(17)
	v_lshlrev_b32_e32 v68, 16, v171
	v_pk_fma_f32 v[56:57], v[106:107], v[70:71], v[56:57]
	v_and_b32_e32 v69, 0xffff0000, v171
	v_pk_fma_f32 v[56:57], v[108:109], v[64:65], v[56:57]
	s_nop 0
	v_pk_fma_f32 v[56:57], v[110:111], v[68:69], v[56:57]
	s_nop 0
	v_cvt_pk_bf16_f32 v55, v56, v57
	v_pk_fma_f32 v[56:57], v[104:105], v[70:71], v[100:101]
	s_waitcnt vmcnt(16)
	v_lshlrev_b32_e32 v70, 16, v172
	v_pk_fma_f32 v[56:57], v[106:107], v[64:65], v[56:57]
	v_and_b32_e32 v71, 0xffff0000, v172
	v_pk_fma_f32 v[56:57], v[108:109], v[68:69], v[56:57]
	s_nop 0
	v_pk_fma_f32 v[56:57], v[110:111], v[70:71], v[56:57]
	s_nop 0
	v_cvt_pk_bf16_f32 v56, v56, v57
	ds_write2_b32 v123, v55, v56 offset0:144 offset1:216
	v_pk_fma_f32 v[56:57], v[104:105], v[64:65], v[100:101]
	s_waitcnt vmcnt(15)
	v_lshlrev_b32_e32 v64, 16, v173
	v_pk_fma_f32 v[56:57], v[106:107], v[68:69], v[56:57]
	v_and_b32_e32 v65, 0xffff0000, v173
	v_pk_fma_f32 v[56:57], v[108:109], v[70:71], v[56:57]
	s_nop 0
	v_pk_fma_f32 v[56:57], v[110:111], v[64:65], v[56:57]
	s_nop 0
	v_cvt_pk_bf16_f32 v55, v56, v57
	v_pk_fma_f32 v[56:57], v[104:105], v[68:69], v[100:101]
	s_waitcnt vmcnt(14)
	v_lshlrev_b32_e32 v68, 16, v174
	v_pk_fma_f32 v[56:57], v[106:107], v[70:71], v[56:57]
	v_and_b32_e32 v69, 0xffff0000, v174
	v_pk_fma_f32 v[56:57], v[108:109], v[64:65], v[56:57]
	s_nop 0
	v_pk_fma_f32 v[56:57], v[110:111], v[68:69], v[56:57]
	s_nop 0
	v_cvt_pk_bf16_f32 v56, v56, v57
	ds_write2_b32 v54, v55, v56 offset0:32 offset1:104
	v_pk_fma_f32 v[56:57], v[104:105], v[70:71], v[100:101]
	s_waitcnt vmcnt(13)
	v_lshlrev_b32_e32 v70, 16, v175
	v_pk_fma_f32 v[56:57], v[106:107], v[64:65], v[56:57]
	v_and_b32_e32 v71, 0xffff0000, v175
	v_pk_fma_f32 v[56:57], v[108:109], v[68:69], v[56:57]
	s_nop 0
	v_pk_fma_f32 v[56:57], v[110:111], v[70:71], v[56:57]
	s_nop 0
	v_cvt_pk_bf16_f32 v55, v56, v57
	v_pk_fma_f32 v[56:57], v[104:105], v[64:65], v[100:101]
	s_waitcnt vmcnt(12)
	v_lshlrev_b32_e32 v64, 16, v176
	v_pk_fma_f32 v[56:57], v[106:107], v[68:69], v[56:57]
	v_and_b32_e32 v65, 0xffff0000, v176
	v_pk_fma_f32 v[56:57], v[108:109], v[70:71], v[56:57]
	s_nop 0
	v_pk_fma_f32 v[56:57], v[110:111], v[64:65], v[56:57]
	s_nop 0
	v_cvt_pk_bf16_f32 v56, v56, v57
	ds_write2_b32 v54, v55, v56 offset0:176 offset1:248

; #define LAS __attribute__((address_space(3)))
; DI float bf2f(unsigned h) { return __uint_as_float(h << 16); }
; DI void cv_issue_q(const CvJob& j, int idx, int lane, f32x4 (&v)[4], int r0) {
;     const float* W; int K, N, item; bf16* WT; const float* ks; cv_decode(j, idx, W, K, N, WT, ks, item);
;     const int nblk = N / 64, kb = item / nblk, nb = item % nblk, k0 = 64 * kb, n0 = 64 * nb, q = lane >> 4, c16 = lane & 15;
;     const char* ub = (const char*)(W + (size_t)(k0 + r0) * N + n0);
;     const unsigned vo = (unsigned)((16 * q) * N + 4 * c16) * 4u;
; #pragma unroll
;     for (int i = 0; i < 4; ++i) v[i] = *(const f32x4*)(ub + (size_t)i * N * 4 + vo);
; }
; DI void rglru_scan_unit(Frame& F, const Mix0Args& a, int u) {
;     ...
;         if constexpr (CV) { int idx = (n >> 2) * NGW + gw; idx = idx < CV_NIT ? idx : idx - CV_NIT;
;             if constexpr (CQ == 0) cv_issue_q(a.cv, idx, lane, cq0, 0); else if constexpr (CQ == 1) cv_issue_q(a.cv, idx, lane, cq1, 4); else if constexpr (CQ == 2) cv_issue_q(a.cv, idx, lane, cq2, 8); else cv_issue_q(a.cv, idx, lane, cq3, 12); }
;         const f32x4 zero4 = (f32x4){0.f, 0.f, 0.f, 0.f};
;         float av[4], uv[4]; float Aseg = 1.f, Hseg = 0.f;
;         { bf16x8 xf[4], waf[4], wxf[4]; unsigned xcr[4];
; #pragma unroll
;           for (int ks = 0; ks < 4; ++ks) { xf[ks] = *(const LAS bf16x8*)(XCc + (l0_ + fr) * S128 + ks * 64 + fq * 16);
;               waf[ks] = *(const LAS bf16x8*)(WAT + (16 * jtile + fr) * S128 + ks * 64 + fq * 16); wxf[ks] = *(const LAS bf16x8*)(WXT + (16 * jtile + fr) * S128 + ks * 64 + fq * 16); }
; #pragma unroll
;           for (int r = 0; r < 4; ++r) xcr[r] = *(const LAS unsigned short*)(XCc + (l0_ + 4 * fq + r) * S128 + (qq * 32 + jj) * 2);
;           f32x4 R = zero4, I = zero4;
; #pragma unroll
;           for (int ks = 0; ks < 4; ++ks) { R = __builtin_amdgcn_mfma_f32_16x16x32_bf16(xf[ks], waf[ks], R, 0, 0, 0); I = __builtin_amdgcn_mfma_f32_16x16x32_bf16(xf[ks], wxf[ks], I, 0, 0, 0); }
; #pragma unroll
;           for (int r = 0; r < 4; ++r) {
;               const float rr = fsigmoid(R[r] + bav), ig = fsigmoid(I[r] + bxv);
;               const float aa = fexp2(-sp8l2 * rr); const float om = __builtin_fmaf(-aa, aa, 1.0f);
;               av[r] = aa; uv[r] = __builtin_sqrtf(om) * (ig * bf2f(xcr[r]));
;               Hseg = aa * Hseg + uv[r]; Aseg *= aa; } }
.LBB0_302:
	s_lshr_b32 s41, s40, 6
	v_cvt_f32_u32_e32 v50, s41
	s_sub_i32 s84, 0, s41
	s_abs_i32 s79, s87
	s_ashr_i32 s78, s87, 31
	v_rcp_iflag_f32_e32 v50, v50
	v_mul_u32_u24_e32 v76, s40, v102
	v_or_b32_e32 v80, v76, v125
	v_lshlrev_b32_e32 v82, 2, v80
	v_mul_f32_e32 v50, 0x4f7ffffe, v50
	v_cvt_u32_f32_e32 v50, v50
	v_lshlrev_b32_e32 v71, 16, v71
	v_lshlrev_b32_e32 v69, 16, v69
	ds_read_b128 v[54:57], v103 offset:36864
	v_readfirstlane_b32 s88, v50
	ds_read_b128 v[50:53], v164 offset:18432
	s_mul_i32 s84, s84, s88
	s_mul_hi_u32 s84, s88, s84
	s_add_i32 s88, s88, s84
	s_mul_hi_u32 s84, s79, s88
	s_mul_i32 s88, s84, s41
	s_sub_i32 s79, s79, s88
	s_add_i32 s89, s84, 1
	s_sub_i32 s88, s79, s41
	s_cmp_ge_u32 s79, s41
	ds_read_b128 v[58:61], v103 offset:46080
	ds_read_b128 v[62:65], v164 offset:18496
	ds_read_b128 v[72:75], v103 offset:36928
	ds_read_b128 v[76:79], v103 offset:46144
	ds_read_b128 v[182:185], v164 offset:18560
	s_cselect_b32 s84, s89, s84
	s_waitcnt lgkmcnt(5)
	v_mfma_f32_16x16x32_bf16 v[54:57], v[50:53], v[54:57], 0
	s_cselect_b32 s79, s88, s79
	s_add_i32 s88, s84, 1
	s_cmp_ge_u32 s79, s41
	s_cselect_b32 s79, s88, s84
	s_waitcnt lgkmcnt(4)
	v_mfma_f32_16x16x32_bf16 v[50:53], v[50:53], v[58:61], 0
	s_xor_b32 s79, s79, s78
	s_sub_i32 s78, s79, s78
	s_mul_i32 s41, s78, s41
	s_waitcnt lgkmcnt(2)
	v_mfma_f32_16x16x32_bf16 v[54:57], v[62:65], v[72:75], v[54:57]
	ds_read_b128 v[58:61], v103 offset:36992
	ds_read_b128 v[72:75], v164 offset:18624
	s_lshl_b32 s78, s78, 6
	s_or_b32 s79, s78, 12
	s_waitcnt lgkmcnt(3)
	v_mfma_f32_16x16x32_bf16 v[50:53], v[62:65], v[76:79], v[50:53]
	ds_read_b128 v[76:79], v103 offset:37056
	s_sub_i32 s41, s87, s41
	s_mul_hi_i32 s89, s79, s40
	s_mul_i32 s88, s79, s40
	s_waitcnt lgkmcnt(2)
	v_mfma_f32_16x16x32_bf16 v[54:57], v[182:185], v[58:61], v[54:57]
	s_lshl_b32 s78, s41, 6
	s_lshl_b64 s[88:89], s[88:89], 2
	s_add_u32 s41, s36, s88
	s_addc_u32 s84, s37, s89
	s_ashr_i32 s79, s78, 31
	s_lshl_b64 s[36:37], s[78:79], 2
	s_waitcnt lgkmcnt(0)
	v_mfma_f32_16x16x32_bf16 v[76:79], v[72:75], v[76:79], v[54:57]
	s_add_u32 s36, s41, s36
	s_addc_u32 s37, s84, s37
	s_lshl_b32 s96, s40, 2
	v_lshl_add_u64 v[80:81], s[36:37], 0, v[82:83]
	v_lshl_add_u64 v[62:63], v[80:81], 0, s[96:97]
	s_nop 2
	v_add_f32_e32 v54, v165, v76
	v_lshl_add_u64 v[80:81], v[62:63], 0, s[96:97]
	global_load_dwordx4 v[58:61], v[62:63], off nt
	s_nop 0
	global_load_dwordx4 v[62:65], v[80:81], off nt
	ds_read_b128 v[186:189], v103 offset:46208
	ds_read_b128 v[190:193], v103 offset:46272
	v_mul_f32_e32 v54, 0xbfb8aa3b, v54
	v_exp_f32_e32 v54, v54
	s_waitcnt lgkmcnt(1)
	v_mfma_f32_16x16x32_bf16 v[182:185], v[182:185], v[186:189], v[50:53]
	v_lshl_add_u64 v[80:81], v[80:81], 0, s[96:97]
	v_add_f32_e32 v77, v165, v77
	s_nop 0
	v_add_f32_e32 v50, 1.0, v54
	v_rcp_f32_e32 v76, v50
	global_load_dwordx4 v[54:57], v82, s[36:37] nt
	global_load_dwordx4 v[50:53], v[80:81], off nt
	s_waitcnt lgkmcnt(0)
	v_mfma_f32_16x16x32_bf16 v[72:75], v[72:75], v[190:193], v[182:185]
	v_mul_f32_e32 v77, 0xbfb8aa3b, v77
	v_mul_f32_e64 v76, v76, -v168
	v_exp_f32_e32 v82, v76
	v_exp_f32_e32 v77, v77
	ds_read_u16 v81, v177 offset:18432
	ds_read_u16 v122, v177 offset:18720
	ds_read_u16 v124, v177 offset:19008
	ds_read_u16 v126, v177 offset:19296
	v_add_f32_e32 v72, v167, v72
	v_fma_f32 v76, -v82, v82, 1.0
	v_mul_f32_e32 v80, 0x4f800000, v76
	v_cmp_gt_f32_e32 vcc, s42, v76
	v_mul_f32_e32 v72, 0xbfb8aa3b, v72
	v_exp_f32_e32 v72, v72
	v_cndmask_b32_e32 v76, v76, v80, vcc
	v_sqrt_f32_e32 v80, v76
	v_add_f32_e32 v77, 1.0, v77
	v_add_f32_e32 v72, 1.0, v72
	v_rcp_f32_e32 v72, v72
	v_add_u32_e32 v128, -1, v80
	v_fma_f32 v182, -v128, v80, v76
	v_cmp_ge_f32_e64 s[36:37], 0, v182
	v_add_u32_e32 v182, 1, v80
	v_rcp_f32_e32 v77, v77
	v_cndmask_b32_e64 v128, v80, v128, s[36:37]
	v_fma_f32 v80, -v182, v80, v76
	v_cmp_lt_f32_e64 s[36:37], 0, v80
	v_add_f32_e32 v78, v165, v78
	v_mul_f32_e32 v78, 0xbfb8aa3b, v78
	v_cndmask_b32_e64 v80, v128, v182, s[36:37]
	v_mul_f32_e32 v128, 0x37800000, v80
	v_cndmask_b32_e32 v80, v80, v128, vcc
	v_cmp_class_f32_e32 vcc, v76, v158
	v_exp_f32_e32 v78, v78
	v_add_f32_e32 v74, v167, v74
	v_cndmask_b32_e32 v76, v80, v76, vcc
	s_waitcnt lgkmcnt(3)
	v_lshlrev_b32_e32 v80, 16, v81
	v_mul_f32_e32 v72, v72, v80
	v_mul_f32_e32 v128, v72, v76
	v_mul_f32_e64 v72, v77, -v168
	v_exp_f32_e32 v206, v72
	v_add_f32_e32 v72, v167, v73
	v_mul_f32_e32 v72, 0xbfb8aa3b, v72
	v_exp_f32_e32 v72, v72
	v_fma_f32 v73, -v206, v206, 1.0
	v_mul_f32_e32 v76, 0x4f800000, v73
	v_cmp_gt_f32_e32 vcc, s42, v73
	v_add_f32_e32 v72, 1.0, v72
	v_add_f32_e32 v78, 1.0, v78
	v_cndmask_b32_e32 v73, v73, v76, vcc
	v_sqrt_f32_e32 v76, v73
	v_rcp_f32_e32 v72, v72
	v_rcp_f32_e32 v78, v78
	v_fma_f32 v77, 0, v82, v128
	v_add_u32_e32 v80, -1, v76
	v_fma_f32 v81, -v80, v76, v73
	v_cmp_ge_f32_e64 s[36:37], 0, v81
	v_add_u32_e32 v81, 1, v76
	v_mul_f32_e32 v74, 0xbfb8aa3b, v74
	v_cndmask_b32_e64 v80, v76, v80, s[36:37]
	v_fma_f32 v76, -v81, v76, v73
	v_cmp_lt_f32_e64 s[36:37], 0, v76
	v_exp_f32_e32 v74, v74
	v_add_f32_e32 v79, v165, v79
	v_cndmask_b32_e64 v76, v80, v81, s[36:37]
	v_mul_f32_e32 v80, 0x37800000, v76
	v_cndmask_b32_e32 v76, v76, v80, vcc
	v_cmp_class_f32_e32 vcc, v73, v158
	v_mul_f32_e32 v79, 0xbfb8aa3b, v79
	v_exp_f32_e32 v79, v79
	v_cndmask_b32_e32 v73, v76, v73, vcc
	s_waitcnt lgkmcnt(2)
; #define LAS __attribute__((address_space(3)))
; DI float bf2f(unsigned h) { return __uint_as_float(h << 16); }
; DI unsigned pk2(float lo, float hi) { f32x2 v = {lo, hi}; bf16v2 b = __builtin_convertvector(v, bf16v2); return __builtin_bit_cast(unsigned, b); }
; DI float fsilu(float x) { return x * fsigmoid(x); }
; #define LDS_BAR() do { asm volatile("s_waitcnt lgkmcnt(0)" ::: "memory"); __builtin_amdgcn_s_barrier(); asm volatile("" ::: "memory"); } while (0)
; DI void rglru_scan_unit(Frame& F, const Mix0Args& a, int u) {
;     ...
;         const int sgi = ltile * 4 + fq;
;         SEGA[jj * 20 + sgi] = Aseg; SEGH[jj * 20 + sgi] = Hseg;
;         LDS_BAR();
;         float carry = HPREV[jj * 20 + (n & 1)]; float sa[15], sh[15];
;         { f32x4 a4[4], h4[4];
; #pragma unroll
;           for (int i = 0; i < 4; ++i) { a4[i] = *(const LAS f32x4*)(SEGA + jj * 20 + 4 * i); h4[i] = *(const LAS f32x4*)(SEGH + jj * 20 + 4 * i); }
; #pragma unroll
;           for (int s = 0; s < 15; ++s) { sa[s] = a4[s >> 2][s & 3]; sh[s] = h4[s >> 2][s & 3]; } }
; #pragma unroll
;         for (int s = 0; s < 15; ++s) carry = (s < sgi) ? sa[s] * carry + sh[s] : carry;
; #pragma unroll
;         for (int r = 0; r < 4; ++r) { carry = av[r] * carry + uv[r];
;             const float o = carry * fsilu(bf2f(gb_cur[r]));
;             obcol[(row0 + l0_ + 4 * fq + r) * a.out_ld] = (bf16)(pk2(o, 0.f) & 0xffffu); }
;         if (sgi == 15) HPREV[jj * 20 + ((n + 1) & 1)] = carry;
;     };
;     int n = 0;
;     for (; n < 4 * nsl; n += 4) { rg_step(n, CvQ<0>{}); rg_step(n + 1, CvQ<1>{}); rg_step(n + 2, CvQ<2>{}); rg_step(n + 3, CvQ<3>{}); }
	v_lshlrev_b32_e32 v76, 16, v122
	v_mul_f32_e32 v72, v72, v76
	v_mul_f32_e64 v76, v78, -v168
	v_exp_f32_e32 v122, v76
	v_mul_f32_e32 v73, v72, v73
	v_fma_f32 v72, v206, v77, v73
	v_add_f32_e32 v74, 1.0, v74
	v_fma_f32 v76, -v122, v122, 1.0
	v_mul_f32_e32 v77, 0x4f800000, v76
	v_cmp_gt_f32_e32 vcc, s42, v76
	v_rcp_f32_e32 v74, v74
	v_add_f32_e32 v79, 1.0, v79
	v_cndmask_b32_e32 v76, v76, v77, vcc
	v_sqrt_f32_e32 v77, v76
	v_rcp_f32_e32 v79, v79
	v_mul_f32_e32 v78, v82, v206
	v_add_u32_e32 v80, -1, v77
	v_fma_f32 v81, -v80, v77, v76
	v_cmp_ge_f32_e64 s[36:37], 0, v81
	v_add_u32_e32 v81, 1, v77
	s_nop 0
	v_cndmask_b32_e64 v80, v77, v80, s[36:37]
	v_fma_f32 v77, -v81, v77, v76
	v_cmp_lt_f32_e64 s[36:37], 0, v77
	s_nop 1
	v_cndmask_b32_e64 v77, v80, v81, s[36:37]
	v_mul_f32_e32 v80, 0x37800000, v77
	v_cndmask_b32_e32 v77, v77, v80, vcc
	v_cmp_class_f32_e32 vcc, v76, v158
	s_nop 1
	v_cndmask_b32_e32 v76, v77, v76, vcc
	s_waitcnt lgkmcnt(1)
	v_lshlrev_b32_e32 v77, 16, v124
	v_mul_f32_e32 v74, v74, v77
	v_mul_f32_e32 v124, v74, v76
	v_fma_f32 v74, v122, v72, v124
	v_mul_f32_e64 v72, v79, -v168
	v_exp_f32_e32 v207, v72
	v_add_f32_e32 v72, v167, v75
	v_mul_f32_e32 v72, 0xbfb8aa3b, v72
	v_exp_f32_e32 v72, v72
	v_fma_f32 v75, -v207, v207, 1.0
	v_mul_f32_e32 v76, 0x4f800000, v75
	v_cmp_gt_f32_e32 vcc, s42, v75
	v_mul_f32_e32 v77, v122, v78
	v_add_f32_e32 v72, 1.0, v72
	v_cndmask_b32_e32 v75, v75, v76, vcc
	v_sqrt_f32_e32 v76, v75
	v_rcp_f32_e32 v72, v72
	v_add_u32_e32 v78, -1, v76
	v_fma_f32 v79, -v78, v76, v75
	v_cmp_ge_f32_e64 s[36:37], 0, v79
	v_add_u32_e32 v79, 1, v76
	s_nop 0
	v_cndmask_b32_e64 v78, v76, v78, s[36:37]
	v_fma_f32 v76, -v79, v76, v75
	v_cmp_lt_f32_e64 s[36:37], 0, v76
	s_nop 1
	v_cndmask_b32_e64 v76, v78, v79, s[36:37]
	v_mul_f32_e32 v78, 0x37800000, v76
	v_cndmask_b32_e32 v76, v76, v78, vcc
	v_cmp_class_f32_e32 vcc, v75, v158
	s_mov_b32 s36, 0x25c00000
	s_nop 0
	v_cndmask_b32_e32 v75, v76, v75, vcc
	s_waitcnt lgkmcnt(0)
	v_lshlrev_b32_e32 v76, 16, v126
	v_mul_f32_e32 v72, v72, v76
	v_mul_f32_e32 v72, v72, v75
	v_fma_f32 v74, v207, v74, v72
	v_mul_f32_e32 v75, v207, v77
	ds_write2st64_b32 v150, v75, v74 offset0:236 offset1:246
	s_waitcnt lgkmcnt(0)
	s_barrier
	ds_read_b32 v126, v149 offset:55364
	ds_read_b128 v[74:77], v149 offset:60416
	ds_read_b128 v[78:81], v149 offset:62976
	ds_read_b128 v[182:185], v149 offset:60432
	ds_read_b128 v[186:189], v149 offset:60448
	ds_read_b128 v[190:193], v149 offset:62992
	ds_read_b128 v[194:197], v149 offset:63008
	ds_read_b128 v[198:201], v149 offset:60464
	ds_read_b128 v[202:205], v149 offset:63024
	s_waitcnt lgkmcnt(6)
	v_fma_f32 v74, v126, v74, v78
	v_cndmask_b32_e64 v74, v74, v126, s[10:11]
	v_fma_f32 v75, v75, v74, v79
	v_cndmask_b32_e64 v74, v74, v75, s[12:13]
	v_fma_f32 v75, v76, v74, v80
	v_cndmask_b32_e64 v74, v74, v75, s[14:15]
	v_fmac_f32_e32 v81, v77, v74
	v_cndmask_b32_e64 v74, v81, v74, s[0:1]
	s_waitcnt lgkmcnt(3)
	v_fma_f32 v75, v182, v74, v190
	v_cndmask_b32_e64 v74, v74, v75, s[16:17]
	v_fma_f32 v75, v183, v74, v191
	v_cndmask_b32_e64 v74, v74, v75, s[18:19]
	v_fma_f32 v75, v184, v74, v192
	v_cndmask_b32_e64 v74, v74, v75, s[20:21]
	v_fmac_f32_e32 v193, v185, v74
	v_cndmask_b32_e64 v74, v74, v193, s[38:39]
	s_waitcnt lgkmcnt(2)
	v_fma_f32 v75, v186, v74, v194
	v_cndmask_b32_e64 v74, v74, v75, s[22:23]
	v_fma_f32 v75, v187, v74, v195
	v_cndmask_b32_e64 v74, v74, v75, s[24:25]
	v_fma_f32 v75, v188, v74, v196
	v_cndmask_b32_e64 v74, v74, v75, s[26:27]
	v_fmac_f32_e32 v197, v189, v74
	v_mul_f32_e32 v76, 0xbfb8aa3b, v71
	v_cndmask_b32_e64 v74, v74, v197, s[4:5]
	v_exp_f32_e32 v76, v76
	s_waitcnt lgkmcnt(0)
	v_fma_f32 v75, v198, v74, v202
	v_cndmask_b32_e64 v74, v74, v75, s[28:29]
	v_fma_f32 v75, v199, v74, v203
	v_cndmask_b32_e64 v74, v74, v75, s[30:31]
	v_add_f32_e32 v75, 1.0, v76
	v_rcp_f32_e32 v75, v75
	v_fmac_f32_e32 v204, v200, v74
	v_cndmask_b32_e64 v74, v74, v204, s[34:35]
	v_fmac_f32_e32 v128, v82, v74
	v_mul_f32_e32 v71, v75, v71
	v_lshlrev_b32_e32 v75, 16, v70
	v_mul_f32_e32 v70, 0xbfb8aa3b, v75
	v_exp_f32_e32 v76, v70
	v_mul_f32_e32 v71, v71, v128
	v_add_co_u32_e32 v70, vcc, s36, v66
	v_cvt_pk_bf16_f32 v74, v71, s0
	s_nop 0
	v_addc_co_u32_e32 v71, vcc, 0, v67, vcc
	global_store_short v[70:71], v74, off
	v_add_f32_e32 v70, 1.0, v76
	v_rcp_f32_e32 v70, v70
	v_mul_f32_e32 v71, 0xbfb8aa3b, v69
	v_exp_f32_e32 v71, v71
	v_fmac_f32_e32 v73, v206, v128
	v_mul_f32_e32 v70, v70, v75
	v_mul_f32_e32 v70, v70, v73
	v_cvt_pk_bf16_f32 v74, v70, s0
	v_add_f32_e32 v70, 1.0, v71
	s_mov_b32 s36, 0x25c0c000
	v_rcp_f32_e32 v75, v70
	v_add_co_u32_e32 v70, vcc, s36, v66
	v_fmac_f32_e32 v124, v122, v73
	s_nop 0
	v_addc_co_u32_e32 v71, vcc, 0, v67, vcc
	global_store_short v[70:71], v74, off
	v_lshlrev_b32_e32 v70, 16, v68
	v_mul_f32_e32 v68, 0xbfb8aa3b, v70
	v_exp_f32_e32 v71, v68
	v_mul_f32_e32 v69, v75, v69
	v_mul_f32_e32 v69, v69, v124
	v_cvt_pk_bf16_f32 v73, v69, s0
	v_add_f32_e32 v69, 1.0, v71
	v_rcp_f32_e32 v71, v69
	s_mov_b32 s36, 0x25c18000
	v_add_co_u32_e32 v68, vcc, s36, v66
	v_fmac_f32_e32 v72, v207, v124
	s_nop 0
	v_addc_co_u32_e32 v69, vcc, 0, v67, vcc
	global_store_short v[68:69], v73, off
	v_mul_f32_e32 v68, v71, v70
	v_mul_f32_e32 v68, v68, v72
	s_mov_b64 s[100:101], 0x25c24000
	v_lshl_add_u64 v[66:67], v[66:67], 0, s[100:101]
	v_cvt_pk_bf16_f32 v68, v68, s0
	global_store_short v[66:67], v68, off
	s_and_saveexec_b64 s[36:37], s[34:35]
	s_cbranch_execz .LBB0_248
	ds_write_b32 v149, v72 offset:55360
	s_branch .LBB0_248

; #define LAS __attribute__((address_space(3)))
; DI void cv_finish(const CvJob& j, int idx, int lane, const f32x4 (&q0)[4], const f32x4 (&q1)[4], const f32x4 (&q2)[4], const f32x4 (&q3)[4], LAS uchar* scr) {
;     const float* W; int K, N, item; bf16* WT; const float* ks; cv_decode(j, idx, W, K, N, WT, ks, item);
;     const int nblk = N / 64, kb = item / nblk, nb = item % nblk, k0 = 64 * kb, n0 = 64 * nb, q = lane >> 4, c16 = lane & 15;
;     f32x4 v[16], kv[4];
;     if (ks) {
; #pragma unroll
;         for (int i = 0; i < 4; ++i) kv[i] = *(const f32x4*)(ks + k0 + 16 * q + 4 * i); }
;     else {
; #pragma unroll
;         for (int i = 0; i < 4; ++i) kv[i] = (f32x4){1.f, 1.f, 1.f, 1.f}; }
; #pragma unroll
;     for (int i = 0; i < 16; ++i) v[i] = (i < 4 ? q0[i & 3] : i < 8 ? q1[i & 3] : i < 12 ? q2[i & 3] : q3[i & 3]) * kv[i >> 2][i & 3];
; DI void rglru_scan_unit(Frame& F, const Mix0Args& a, int u) {
;     ...
;     if (nsl > 0 && (nsl - 1) * NGW + gw < CV_NIT) cv_finish(a.cv, (nsl - 1) * NGW + gw, lane, cq0, cq1, cq2, cq3, CVS);
.LBB0_315:
	v_cvt_f32_u32_e32 v66, s76
	s_sub_i32 s41, 0, s76
	s_abs_i32 s40, s3
	s_ashr_i32 s9, s3, 31
	v_rcp_iflag_f32_e32 v66, v66
	s_nop 0
	v_mul_f32_e32 v66, 0x4f7ffffe, v66
	v_cvt_u32_f32_e32 v66, v66
	s_nop 0
	v_readfirstlane_b32 s77, v66
	s_mul_i32 s41, s41, s77
	s_mul_hi_u32 s41, s77, s41
	s_add_i32 s77, s77, s41
	s_mul_hi_u32 s41, s40, s77
	s_mul_i32 s77, s41, s76
	s_sub_i32 s40, s40, s77
	s_add_i32 s84, s41, 1
	s_sub_i32 s77, s40, s76
	s_cmp_ge_u32 s40, s76
	s_cselect_b32 s41, s84, s41
	s_cselect_b32 s40, s77, s40
	s_add_i32 s77, s41, 1
	s_cmp_ge_u32 s40, s76
	s_cselect_b32 s40, s77, s41
	s_xor_b32 s40, s40, s9
	s_sub_i32 s9, s40, s9
	s_lshl_b32 s40, s9, 6
	s_ashr_i32 s41, s40, 31
	s_cmp_eq_u64 s[78:79], 0
	s_cbranch_scc1 .LBB0_317
	s_lshl_b64 s[86:87], s[40:41], 2
	s_add_u32 s78, s78, s86
	s_addc_u32 s79, s79, s87
	v_lshlrev_b32_e32 v66, 2, v102
	global_load_dwordx4 v[78:81], v66, s[78:79] offset:48 nt
	global_load_dwordx4 v[74:77], v66, s[78:79] offset:32 nt
	global_load_dwordx4 v[70:73], v66, s[78:79] offset:16 nt
	s_nop 0
	global_load_dwordx4 v[66:69], v66, s[78:79] nt
	s_waitcnt vmcnt(3)
	v_mov_b32_e32 v128, v79
	v_mov_b32_e32 v82, v81
	s_waitcnt vmcnt(2)
	v_mov_b32_e32 v124, v75
	v_mov_b32_e32 v126, v77
	s_waitcnt vmcnt(1)
	v_mov_b32_e32 v120, v71
	v_mov_b32_e32 v122, v73
	s_waitcnt vmcnt(0)
	v_mov_b32_e32 v116, v67
	v_mov_b32_e32 v118, v69
	s_branch .LBB0_318

; #define LAS __attribute__((address_space(3)))
; DI unsigned pk2(float lo, float hi) { f32x2 v = {lo, hi}; bf16v2 b = __builtin_convertvector(v, bf16v2); return __builtin_bit_cast(unsigned, b); }
; DI void cv_finish(const CvJob& j, int idx, int lane, const f32x4 (&q0)[4], const f32x4 (&q1)[4], const f32x4 (&q2)[4], const f32x4 (&q3)[4], LAS uchar* scr) {
;     ...
;     for (int i = 0; i < 16; ++i) v[i] = (i < 4 ? q0[i & 3] : i < 8 ? q1[i & 3] : i < 12 ? q2[i & 3] : q3[i & 3]) * kv[i >> 2][i & 3];
; #pragma unroll
;     for (int jj = 0; jj < 4; ++jj) { u32x4 lo, hi;
;         lo.x = pk2(v[0][jj], v[1][jj]); lo.y = pk2(v[2][jj], v[3][jj]); lo.z = pk2(v[4][jj], v[5][jj]); lo.w = pk2(v[6][jj], v[7][jj]);
;         hi.x = pk2(v[8][jj], v[9][jj]); hi.y = pk2(v[10][jj], v[11][jj]); hi.z = pk2(v[12][jj], v[13][jj]); hi.w = pk2(v[14][jj], v[15][jj]);
;         LAS uchar* p = scr + (4 * c16 + jj) * TSTR + q * 32; *(LAS u32x4*)p = lo; *(LAS u32x4*)(p + 16) = hi; }
;     asm volatile("s_waitcnt lgkmcnt(0)" ::: "memory");
;     const int c = lane & 7, nr = lane >> 3;
; #pragma unroll
;     for (int hf = 0; hf < 2; ++hf) {
; #pragma unroll
;         for (int r = 4 * hf; r < 4 * hf + 4; ++r) { const int n = nr + 8 * r;
;             *(u32x4*)(WT + (size_t)(n0 + n) * K + k0 + 8 * c) = *(const LAS u32x4*)(scr + n * TSTR + c * 16); }
;         asm volatile("s_waitcnt lgkmcnt(0)" ::: "memory"); }
; }
.LBB0_318:
	v_pk_mul_f32 v[30:31], v[30:31], v[122:123] op_sel_hi:[1,0]
	v_pk_mul_f32 v[28:29], v[28:29], v[72:73] op_sel_hi:[1,0]
	v_pk_mul_f32 v[26:27], v[26:27], v[72:73] op_sel_hi:[1,0]
	v_pk_mul_f32 v[22:23], v[22:23], v[120:121] op_sel_hi:[1,0]
	v_pk_mul_f32 v[20:21], v[20:21], v[70:71] op_sel_hi:[1,0]
	v_pk_mul_f32 v[18:19], v[18:19], v[70:71] op_sel_hi:[1,0]
	v_pk_mul_f32 v[14:15], v[14:15], v[118:119] op_sel_hi:[1,0]
	v_pk_mul_f32 v[10:11], v[10:11], v[68:69] op_sel_hi:[1,0]
	v_pk_mul_f32 v[70:71], v[6:7], v[116:117] op_sel_hi:[1,0]
	v_pk_mul_f32 v[72:73], v[4:5], v[66:67] op_sel_hi:[1,0]
	v_pk_mul_f32 v[66:67], v[2:3], v[66:67] op_sel_hi:[1,0]
	s_waitcnt vmcnt(6)
	v_pk_mul_f32 v[62:63], v[62:63], v[80:81] op_sel_hi:[1,0]
	v_pk_mul_f32 v[58:59], v[58:59], v[128:129] op_sel_hi:[1,0]
	s_waitcnt vmcnt(5)
	v_pk_mul_f32 v[54:55], v[54:55], v[78:79] op_sel_hi:[1,0]
	v_pk_mul_f32 v[46:47], v[46:47], v[126:127] op_sel_hi:[1,0]
	v_pk_mul_f32 v[42:43], v[42:43], v[76:77] op_sel_hi:[1,0]
	v_pk_mul_f32 v[38:39], v[38:39], v[124:125] op_sel_hi:[1,0]
	v_pk_mul_f32 v[34:35], v[34:35], v[74:75] op_sel_hi:[1,0]
	s_waitcnt vmcnt(4)
	v_pk_mul_f32 v[50:51], v[50:51], v[82:83] op_sel_hi:[1,0]
	v_cvt_pk_bf16_f32 v2, v66, v70
	v_cvt_pk_bf16_f32 v3, v10, v14
	v_cvt_pk_bf16_f32 v4, v18, v22
	v_cvt_pk_bf16_f32 v5, v26, v30
	v_add_u32_e32 v10, v127, v129
	v_pk_mul_f32 v[32:33], v[32:33], v[122:123] op_sel_hi:[1,0]
	v_pk_mul_f32 v[24:25], v[24:25], v[120:121] op_sel_hi:[1,0]
	v_pk_mul_f32 v[16:17], v[16:17], v[118:119] op_sel_hi:[1,0]
	v_pk_mul_f32 v[12:13], v[12:13], v[68:69] op_sel_hi:[1,0]
	v_pk_mul_f32 v[68:69], v[8:9], v[116:117] op_sel_hi:[1,0]
	v_cvt_pk_bf16_f32 v6, v34, v38
	v_cvt_pk_bf16_f32 v7, v42, v46
	v_cvt_pk_bf16_f32 v8, v54, v58
	v_cvt_pk_bf16_f32 v9, v62, v50
	ds_write_b128 v10, v[2:5]
	ds_write_b128 v10, v[6:9] offset:16
	v_cvt_pk_bf16_f32 v2, v67, v71
	v_cvt_pk_bf16_f32 v3, v11, v15
	v_cvt_pk_bf16_f32 v4, v19, v23
	v_cvt_pk_bf16_f32 v5, v27, v31
	v_pk_mul_f32 v[64:65], v[64:65], v[80:81] op_sel_hi:[1,0]
	v_pk_mul_f32 v[60:61], v[60:61], v[128:129] op_sel_hi:[1,0]
	v_pk_mul_f32 v[56:57], v[56:57], v[78:79] op_sel_hi:[1,0]
	v_pk_mul_f32 v[48:49], v[48:49], v[126:127] op_sel_hi:[1,0]
	v_pk_mul_f32 v[44:45], v[44:45], v[76:77] op_sel_hi:[1,0]
	v_pk_mul_f32 v[40:41], v[40:41], v[124:125] op_sel_hi:[1,0]
	v_pk_mul_f32 v[36:37], v[36:37], v[74:75] op_sel_hi:[1,0]
	v_pk_mul_f32 v[52:53], v[52:53], v[82:83] op_sel_hi:[1,0]
	v_cvt_pk_bf16_f32 v6, v35, v39
	v_cvt_pk_bf16_f32 v7, v43, v47
	v_cvt_pk_bf16_f32 v8, v55, v59
	v_cvt_pk_bf16_f32 v9, v63, v51
	ds_write_b128 v10, v[2:5] offset:144
	ds_write_b128 v10, v[6:9] offset:160
	v_cvt_pk_bf16_f32 v2, v72, v68
	v_cvt_pk_bf16_f32 v3, v12, v16
	v_cvt_pk_bf16_f32 v4, v20, v24
	v_cvt_pk_bf16_f32 v5, v28, v32
	s_mul_i32 s9, s9, s76
	v_cvt_pk_bf16_f32 v6, v36, v40
	v_cvt_pk_bf16_f32 v7, v44, v48
	v_cvt_pk_bf16_f32 v8, v56, v60
	v_cvt_pk_bf16_f32 v9, v64, v52
	ds_write_b128 v10, v[2:5] offset:288
	ds_write_b128 v10, v[6:9] offset:304
	v_cvt_pk_bf16_f32 v2, v73, v69
	v_cvt_pk_bf16_f32 v3, v13, v17
	v_cvt_pk_bf16_f32 v4, v21, v25
	v_cvt_pk_bf16_f32 v5, v29, v33
	s_sub_i32 s3, s3, s9
	v_cvt_pk_bf16_f32 v6, v37, v41
	v_cvt_pk_bf16_f32 v7, v45, v49
	v_cvt_pk_bf16_f32 v8, v57, v61
	v_cvt_pk_bf16_f32 v9, v65, v53
	ds_write_b128 v10, v[2:5] offset:432
	ds_write_b128 v10, v[6:9] offset:448
	s_lshl_b32 s3, s3, 6
	s_waitcnt lgkmcnt(0)
	s_lshl_b64 s[40:41], s[40:41], 1
	v_add_u32_e32 v14, v133, v135
	s_add_u32 s36, s36, s40
	ds_read_b128 v[2:5], v14
	s_addc_u32 s37, s37, s41
	v_lshlrev_b32_e32 v82, 1, v92
	v_or_b32_e32 v6, s3, v131
	v_lshl_add_u64 v[10:11], s[36:37], 0, v[82:83]
	v_mad_i64_i32 v[6:7], s[36:37], s8, v6, 0
	v_lshl_add_u64 v[12:13], v[6:7], 1, v[10:11]
	ds_read_b128 v[6:9], v14 offset:1152
	s_waitcnt lgkmcnt(1)
	global_store_dwordx4 v[12:13], v[2:5], off nt
	s_nop 1
	v_or_b32_e32 v2, s3, v136
	v_mad_i64_i32 v[2:3], s[36:37], s8, v2, 0
	v_lshl_add_u64 v[2:3], v[2:3], 1, v[10:11]
	s_waitcnt lgkmcnt(0)
	global_store_dwordx4 v[2:3], v[6:9], off nt
	ds_read_b128 v[2:5], v14 offset:2304
	s_nop 0
	v_or_b32_e32 v6, s3, v137
	v_mad_i64_i32 v[6:7], s[36:37], s8, v6, 0
	v_lshl_add_u64 v[12:13], v[6:7], 1, v[10:11]
	ds_read_b128 v[6:9], v14 offset:3456
	s_waitcnt lgkmcnt(1)
	global_store_dwordx4 v[12:13], v[2:5], off nt
	s_nop 1
	v_or_b32_e32 v2, s3, v138
	v_mad_i64_i32 v[2:3], s[36:37], s8, v2, 0
	v_lshl_add_u64 v[2:3], v[2:3], 1, v[10:11]
	s_waitcnt lgkmcnt(0)
	global_store_dwordx4 v[2:3], v[6:9], off nt
	s_waitcnt lgkmcnt(0)
	ds_read_b128 v[2:5], v14 offset:4608
	s_nop 0
	v_or_b32_e32 v6, s3, v139
	v_mad_i64_i32 v[6:7], s[36:37], s8, v6, 0
	v_lshl_add_u64 v[12:13], v[6:7], 1, v[10:11]
	ds_read_b128 v[6:9], v14 offset:5760
	s_waitcnt lgkmcnt(1)
	global_store_dwordx4 v[12:13], v[2:5], off nt
	s_nop 1
	v_or_b32_e32 v2, s3, v140
	v_mad_i64_i32 v[2:3], s[36:37], s8, v2, 0
	v_lshl_add_u64 v[2:3], v[2:3], 1, v[10:11]
	s_waitcnt lgkmcnt(0)
	global_store_dwordx4 v[2:3], v[6:9], off nt
	ds_read_b128 v[2:5], v14 offset:6912
	s_nop 0
	v_or_b32_e32 v6, s3, v141
	v_mad_i64_i32 v[6:7], s[36:37], s8, v6, 0
	v_lshl_add_u64 v[12:13], v[6:7], 1, v[10:11]
	ds_read_b128 v[6:9], v14 offset:8064
	s_waitcnt lgkmcnt(1)
	global_store_dwordx4 v[12:13], v[2:5], off nt
	s_nop 1
	v_or_b32_e32 v2, s3, v142
	v_mad_i64_i32 v[2:3], s[8:9], s8, v2, 0
	v_lshl_add_u64 v[2:3], v[2:3], 1, v[10:11]
	s_waitcnt lgkmcnt(0)
	global_store_dwordx4 v[2:3], v[6:9], off nt
	s_waitcnt lgkmcnt(0)

; #define LAS __attribute__((address_space(3)))
; DI unsigned pk2(float lo, float hi) { f32x2 v = {lo, hi}; bf16v2 b = __builtin_convertvector(v, bf16v2); return __builtin_bit_cast(unsigned, b); }
; DI void cv_finish(const CvJob& j, int idx, int lane, const f32x4 (&q0)[4], const f32x4 (&q1)[4], const f32x4 (&q2)[4], const f32x4 (&q3)[4], LAS uchar* scr) {
;     const float* W; int K, N, item; bf16* WT; const float* ks; cv_decode(j, idx, W, K, N, WT, ks, item);
;     const int nblk = N / 64, kb = item / nblk, nb = item % nblk, k0 = 64 * kb, n0 = 64 * nb, q = lane >> 4, c16 = lane & 15;
;     f32x4 v[16], kv[4];
;     if (ks) {
; #pragma unroll
;         for (int i = 0; i < 4; ++i) kv[i] = *(const f32x4*)(ks + k0 + 16 * q + 4 * i); }
;     else {
; #pragma unroll
;         for (int i = 0; i < 4; ++i) kv[i] = (f32x4){1.f, 1.f, 1.f, 1.f}; }
; #pragma unroll
;     for (int i = 0; i < 16; ++i) v[i] = (i < 4 ? q0[i & 3] : i < 8 ? q1[i & 3] : i < 12 ? q2[i & 3] : q3[i & 3]) * kv[i >> 2][i & 3];
; #pragma unroll
;     for (int jj = 0; jj < 4; ++jj) { u32x4 lo, hi;
;         lo.x = pk2(v[0][jj], v[1][jj]); lo.y = pk2(v[2][jj], v[3][jj]); lo.z = pk2(v[4][jj], v[5][jj]); lo.w = pk2(v[6][jj], v[7][jj]);
;         hi.x = pk2(v[8][jj], v[9][jj]); hi.y = pk2(v[10][jj], v[11][jj]); hi.z = pk2(v[12][jj], v[13][jj]); hi.w = pk2(v[14][jj], v[15][jj]);
;         LAS uchar* p = scr + (4 * c16 + jj) * TSTR + q * 32; *(LAS u32x4*)p = lo; *(LAS u32x4*)(p + 16) = hi; }
;     asm volatile("s_waitcnt lgkmcnt(0)" ::: "memory");
;     const int c = lane & 7, nr = lane >> 3;
; #pragma unroll
;     for (int hf = 0; hf < 2; ++hf) {
; #pragma unroll
;         for (int r = 4 * hf; r < 4 * hf + 4; ++r) { const int n = nr + 8 * r;
;             *(u32x4*)(WT + (size_t)(n0 + n) * K + k0 + 8 * c) = *(const LAS u32x4*)(scr + n * TSTR + c * 16); }
;         asm volatile("s_waitcnt lgkmcnt(0)" ::: "memory"); }
; }
; DI void rglru_scan_unit(Frame& F, const Mix0Args& a, int u) {
;     ...
;     if (cv_on) for (int sl = NCH / 4; sl * NGW + gw < CV_NIT; ++sl) { const int ix = sl * NGW + gw; cv_issue_q(a.cv, ix, lane, cq0, 0); cv_issue_q(a.cv, ix, lane, cq1, 4); cv_issue_q(a.cv, ix, lane, cq2, 8); cv_issue_q(a.cv, ix, lane, cq3, 12); cv_finish(a.cv, ix, lane, cq0, cq1, cq2, cq3, CVS); }
.LBB0_331:
	s_lshl_b64 s[82:83], s[36:37], 2
	s_add_u32 s40, s40, s82
	s_addc_u32 s41, s41, s83
	v_lshlrev_b32_e32 v66, 2, v102
	global_load_dwordx4 v[78:81], v66, s[40:41] offset:48 nt
	global_load_dwordx4 v[74:77], v66, s[40:41] offset:32 nt
	global_load_dwordx4 v[70:73], v66, s[40:41] offset:16 nt
	s_nop 0
	global_load_dwordx4 v[66:69], v66, s[40:41] nt
	s_waitcnt vmcnt(3)
	v_mov_b32_e32 v112, v79
	v_mov_b32_e32 v82, v81
	s_waitcnt vmcnt(2)
	v_mov_b32_e32 v108, v75
	v_mov_b32_e32 v114, v77
	s_waitcnt vmcnt(1)
	v_mov_b32_e32 v104, v71
	v_mov_b32_e32 v110, v73
	s_waitcnt vmcnt(0)
	v_mov_b32_e32 v100, v67
	v_mov_b32_e32 v106, v69
.LBB0_332:
	s_waitcnt vmcnt(8)
	v_pk_mul_f32 v[30:31], v[30:31], v[110:111] op_sel_hi:[1,0]
	v_pk_mul_f32 v[28:29], v[28:29], v[72:73] op_sel_hi:[1,0]
	v_pk_mul_f32 v[26:27], v[26:27], v[72:73] op_sel_hi:[1,0]
	v_pk_mul_f32 v[22:23], v[22:23], v[104:105] op_sel_hi:[1,0]
	v_pk_mul_f32 v[20:21], v[20:21], v[70:71] op_sel_hi:[1,0]
	v_pk_mul_f32 v[18:19], v[18:19], v[70:71] op_sel_hi:[1,0]
	v_pk_mul_f32 v[14:15], v[14:15], v[106:107] op_sel_hi:[1,0]
	v_pk_mul_f32 v[10:11], v[10:11], v[68:69] op_sel_hi:[1,0]
	v_pk_mul_f32 v[70:71], v[6:7], v[100:101] op_sel_hi:[1,0]
	v_pk_mul_f32 v[72:73], v[4:5], v[66:67] op_sel_hi:[1,0]
	v_pk_mul_f32 v[66:67], v[2:3], v[66:67] op_sel_hi:[1,0]
	s_waitcnt vmcnt(2)
	v_pk_mul_f32 v[62:63], v[62:63], v[80:81] op_sel_hi:[1,0]
	v_pk_mul_f32 v[58:59], v[58:59], v[112:113] op_sel_hi:[1,0]
	s_waitcnt vmcnt(1)
	v_pk_mul_f32 v[54:55], v[54:55], v[78:79] op_sel_hi:[1,0]
	v_pk_mul_f32 v[46:47], v[46:47], v[114:115] op_sel_hi:[1,0]
	v_pk_mul_f32 v[42:43], v[42:43], v[76:77] op_sel_hi:[1,0]
	v_pk_mul_f32 v[38:39], v[38:39], v[108:109] op_sel_hi:[1,0]
	v_pk_mul_f32 v[34:35], v[34:35], v[74:75] op_sel_hi:[1,0]
	s_waitcnt vmcnt(0)
	v_pk_mul_f32 v[50:51], v[50:51], v[82:83] op_sel_hi:[1,0]
	v_cvt_pk_bf16_f32 v2, v66, v70
	v_cvt_pk_bf16_f32 v3, v10, v14
	v_cvt_pk_bf16_f32 v4, v18, v22
	v_cvt_pk_bf16_f32 v5, v26, v30
	v_add_u32_e32 v10, v127, v129
	v_pk_mul_f32 v[32:33], v[32:33], v[110:111] op_sel_hi:[1,0]
	v_pk_mul_f32 v[24:25], v[24:25], v[104:105] op_sel_hi:[1,0]
	v_pk_mul_f32 v[16:17], v[16:17], v[106:107] op_sel_hi:[1,0]
	v_pk_mul_f32 v[12:13], v[12:13], v[68:69] op_sel_hi:[1,0]
	v_pk_mul_f32 v[68:69], v[8:9], v[100:101] op_sel_hi:[1,0]
	v_cvt_pk_bf16_f32 v6, v34, v38
	v_cvt_pk_bf16_f32 v7, v42, v46
	v_cvt_pk_bf16_f32 v8, v54, v58
	v_cvt_pk_bf16_f32 v9, v62, v50
	ds_write_b128 v10, v[2:5]
	ds_write_b128 v10, v[6:9] offset:16
	v_cvt_pk_bf16_f32 v2, v67, v71
	v_cvt_pk_bf16_f32 v3, v11, v15
	v_cvt_pk_bf16_f32 v4, v19, v23
	v_cvt_pk_bf16_f32 v5, v27, v31
	v_pk_mul_f32 v[64:65], v[64:65], v[80:81] op_sel_hi:[1,0]
	v_pk_mul_f32 v[60:61], v[60:61], v[112:113] op_sel_hi:[1,0]
	v_pk_mul_f32 v[56:57], v[56:57], v[78:79] op_sel_hi:[1,0]
	v_pk_mul_f32 v[48:49], v[48:49], v[114:115] op_sel_hi:[1,0]
	v_pk_mul_f32 v[44:45], v[44:45], v[76:77] op_sel_hi:[1,0]
	v_pk_mul_f32 v[40:41], v[40:41], v[108:109] op_sel_hi:[1,0]
	v_pk_mul_f32 v[36:37], v[36:37], v[74:75] op_sel_hi:[1,0]
	v_pk_mul_f32 v[52:53], v[52:53], v[82:83] op_sel_hi:[1,0]
	v_cvt_pk_bf16_f32 v6, v35, v39
	v_cvt_pk_bf16_f32 v7, v43, v47
	v_cvt_pk_bf16_f32 v8, v55, v59
	v_cvt_pk_bf16_f32 v9, v63, v51
	ds_write_b128 v10, v[2:5] offset:144
	ds_write_b128 v10, v[6:9] offset:160
	v_cvt_pk_bf16_f32 v2, v72, v68
	v_cvt_pk_bf16_f32 v3, v12, v16
	v_cvt_pk_bf16_f32 v4, v20, v24
	v_cvt_pk_bf16_f32 v5, v28, v32
	s_mul_i32 s3, s3, s78
	v_cvt_pk_bf16_f32 v6, v36, v40
	v_cvt_pk_bf16_f32 v7, v44, v48
	v_cvt_pk_bf16_f32 v8, v56, v60
	v_cvt_pk_bf16_f32 v9, v64, v52
	ds_write_b128 v10, v[2:5] offset:288
	ds_write_b128 v10, v[6:9] offset:304
	v_cvt_pk_bf16_f32 v2, v73, v69
	v_cvt_pk_bf16_f32 v3, v13, v17
	v_cvt_pk_bf16_f32 v4, v21, v25
	v_cvt_pk_bf16_f32 v5, v29, v33
	s_sub_i32 s3, s77, s3
	v_cvt_pk_bf16_f32 v6, v37, v41
	v_cvt_pk_bf16_f32 v7, v45, v49
	v_cvt_pk_bf16_f32 v8, v57, v61
	v_cvt_pk_bf16_f32 v9, v65, v53
	ds_write_b128 v10, v[2:5] offset:432
	ds_write_b128 v10, v[6:9] offset:448
	s_lshl_b32 s3, s3, 6
	s_waitcnt lgkmcnt(0)
	s_lshl_b64 s[36:37], s[36:37], 1
	v_add_u32_e32 v14, v133, v135
	s_add_u32 s8, s8, s36
	ds_read_b128 v[2:5], v14
	s_addc_u32 s9, s9, s37
	v_lshlrev_b32_e32 v82, 1, v92
	v_or_b32_e32 v6, s3, v131
	v_lshl_add_u64 v[10:11], s[8:9], 0, v[82:83]
	v_mad_i64_i32 v[6:7], s[8:9], s2, v6, 0
	v_lshl_add_u64 v[12:13], v[6:7], 1, v[10:11]
	ds_read_b128 v[6:9], v14 offset:1152
	s_waitcnt lgkmcnt(1)
	global_store_dwordx4 v[12:13], v[2:5], off nt
	s_add_i32 s76, s76, s94
	s_cmp_lt_i32 s76, 0x8880
	v_or_b32_e32 v2, s3, v136
	v_mad_i64_i32 v[2:3], s[8:9], s2, v2, 0
	v_lshl_add_u64 v[2:3], v[2:3], 1, v[10:11]
	s_waitcnt lgkmcnt(0)
	global_store_dwordx4 v[2:3], v[6:9], off nt
	ds_read_b128 v[2:5], v14 offset:2304
	s_nop 0
	v_or_b32_e32 v6, s3, v137
	v_mad_i64_i32 v[6:7], s[8:9], s2, v6, 0
	v_lshl_add_u64 v[12:13], v[6:7], 1, v[10:11]
	ds_read_b128 v[6:9], v14 offset:3456
	s_waitcnt lgkmcnt(1)
	global_store_dwordx4 v[12:13], v[2:5], off nt
	s_nop 1
	v_or_b32_e32 v2, s3, v138
	v_mad_i64_i32 v[2:3], s[8:9], s2, v2, 0
	v_lshl_add_u64 v[2:3], v[2:3], 1, v[10:11]
	s_waitcnt lgkmcnt(0)
	global_store_dwordx4 v[2:3], v[6:9], off nt
	s_waitcnt lgkmcnt(0)
	ds_read_b128 v[2:5], v14 offset:4608
	s_nop 0
	v_or_b32_e32 v6, s3, v139
	v_mad_i64_i32 v[6:7], s[8:9], s2, v6, 0
	v_lshl_add_u64 v[12:13], v[6:7], 1, v[10:11]
	ds_read_b128 v[6:9], v14 offset:5760
	s_waitcnt lgkmcnt(1)
	global_store_dwordx4 v[12:13], v[2:5], off nt
	s_nop 1
	v_or_b32_e32 v2, s3, v140
	v_mad_i64_i32 v[2:3], s[8:9], s2, v2, 0
	v_lshl_add_u64 v[2:3], v[2:3], 1, v[10:11]
	s_waitcnt lgkmcnt(0)
	global_store_dwordx4 v[2:3], v[6:9], off nt
	ds_read_b128 v[2:5], v14 offset:6912
	s_nop 0
	v_or_b32_e32 v6, s3, v141
	v_mad_i64_i32 v[6:7], s[8:9], s2, v6, 0
	v_lshl_add_u64 v[12:13], v[6:7], 1, v[10:11]
	ds_read_b128 v[6:9], v14 offset:8064
	s_waitcnt lgkmcnt(1)
	global_store_dwordx4 v[12:13], v[2:5], off nt
	s_nop 1
	v_or_b32_e32 v2, s3, v142
	v_mad_i64_i32 v[2:3], s[2:3], s2, v2, 0
	v_lshl_add_u64 v[2:3], v[2:3], 1, v[10:11]
	s_waitcnt lgkmcnt(0)
	global_store_dwordx4 v[2:3], v[6:9], off nt
	s_waitcnt lgkmcnt(0)
	s_cbranch_scc0 .LBB0_233

; DI void cv_issue_q(const CvJob& j, int idx, int lane, f32x4 (&v)[4], int r0) {
;     const float* W; int K, N, item; bf16* WT; const float* ks; cv_decode(j, idx, W, K, N, WT, ks, item);
;     const int nblk = N / 64, kb = item / nblk, nb = item % nblk, k0 = 64 * kb, n0 = 64 * nb, q = lane >> 4, c16 = lane & 15;
;     const char* ub = (const char*)(W + (size_t)(k0 + r0) * N + n0);
;     const unsigned vo = (unsigned)((16 * q) * N + 4 * c16) * 4u;
; #pragma unroll
;     for (int i = 0; i < 4; ++i) v[i] = *(const f32x4*)(ub + (size_t)i * N * 4 + vo);
; }
; DI void rglru_scan_unit(Frame& F, const Mix0Args& a, int u) {
;     ...
;     if (cv_on) for (int sl = NCH / 4; sl * NGW + gw < CV_NIT; ++sl) { const int ix = sl * NGW + gw; cv_issue_q(a.cv, ix, lane, cq0, 0); cv_issue_q(a.cv, ix, lane, cq1, 4); cv_issue_q(a.cv, ix, lane, cq2, 8); cv_issue_q(a.cv, ix, lane, cq3, 12); cv_finish(a.cv, ix, lane, cq0, cq1, cq2, cq3, CVS); }
.LBB0_338:
	s_lshr_b32 s37, s36, 6
	v_cvt_f32_u32_e32 v2, s37
	s_sub_i32 s79, 0, s37
	s_abs_i32 s78, s41
	s_ashr_i32 s77, s41, 31
	v_rcp_iflag_f32_e32 v2, v2
	v_cndmask_b32_e64 v18, 0, 1, s[2:3]
	v_mul_f32_e32 v2, 0x4f7ffffe, v2
	v_cvt_u32_f32_e32 v2, v2
	s_nop 0
	v_readfirstlane_b32 s82, v2
	s_mul_i32 s79, s79, s82
	s_mul_hi_u32 s79, s82, s79
	s_add_i32 s82, s82, s79
	s_mul_hi_u32 s79, s78, s82
	s_mul_i32 s82, s79, s37
	s_sub_i32 s78, s78, s82
	s_add_i32 s83, s79, 1
	s_sub_i32 s82, s78, s37
	s_cmp_ge_u32 s78, s37
	s_cselect_b32 s79, s83, s79
	s_cselect_b32 s78, s82, s78
	s_add_i32 s82, s79, 1
	s_cmp_ge_u32 s78, s37
	s_cselect_b32 s78, s82, s79
	s_xor_b32 s78, s78, s77
	s_sub_i32 s77, s78, s77
	s_mul_i32 s37, s77, s37
	s_lshl_b32 s77, s77, 6
	s_sub_i32 s37, s41, s37
	s_mul_hi_i32 s79, s77, s36
	s_mul_i32 s78, s77, s36
	s_lshl_b32 s82, s37, 6
	s_lshl_b64 s[78:79], s[78:79], 2
	s_add_u32 s37, s8, s78
	s_addc_u32 s41, s9, s79
	s_ashr_i32 s83, s82, 31
	s_lshl_b64 s[8:9], s[82:83], 2
	v_mul_u32_u24_e32 v2, s36, v102
	s_add_u32 s8, s37, s8
	v_or_b32_e32 v2, v2, v125
	s_addc_u32 s9, s41, s9
	v_lshlrev_b32_e32 v82, 2, v2
	s_lshl_b32 s96, s36, 2
	v_lshl_add_u64 v[2:3], s[8:9], 0, v[82:83]
	v_lshl_add_u64 v[2:3], v[2:3], 0, s[96:97]
	v_lshl_add_u64 v[4:5], v[2:3], 0, s[96:97]
	v_lshl_add_u64 v[14:15], v[4:5], 0, s[96:97]
	global_load_dwordx4 v[6:9], v[2:3], off nt
	global_load_dwordx4 v[10:13], v[4:5], off nt
	s_nop 0
	global_load_dwordx4 v[2:5], v82, s[8:9] nt
	s_nop 0
	global_load_dwordx4 v[14:17], v[14:15], off nt
	v_cmp_ne_u32_e64 s[36:37], 1, v18
	s_andn2_b64 vcc, exec, s[2:3]
	s_mov_b64 s[2:3], s[68:69]
	s_mov_b32 s41, s76
	s_cbranch_vccnz .LBB0_343
	s_cmpk_gt_u32 s76, 0x687f
	s_cbranch_scc0 .LBB0_341
	s_add_i32 s41, s76, 0xffff9780
	s_mov_b64 s[2:3], s[52:53]
	s_cbranch_execz .LBB0_342
	s_branch .LBB0_343

; DI void cv_issue_q(const CvJob& j, int idx, int lane, f32x4 (&v)[4], int r0) {
;     const float* W; int K, N, item; bf16* WT; const float* ks; cv_decode(j, idx, W, K, N, WT, ks, item);
;     const int nblk = N / 64, kb = item / nblk, nb = item % nblk, k0 = 64 * kb, n0 = 64 * nb, q = lane >> 4, c16 = lane & 15;
;     const char* ub = (const char*)(W + (size_t)(k0 + r0) * N + n0);
;     const unsigned vo = (unsigned)((16 * q) * N + 4 * c16) * 4u;
; #pragma unroll
;     for (int i = 0; i < 4; ++i) v[i] = *(const f32x4*)(ub + (size_t)i * N * 4 + vo);
; }
; DI void rglru_scan_unit(Frame& F, const Mix0Args& a, int u) {
;     ...
;     if (cv_on) for (int sl = NCH / 4; sl * NGW + gw < CV_NIT; ++sl) { const int ix = sl * NGW + gw; cv_issue_q(a.cv, ix, lane, cq0, 0); cv_issue_q(a.cv, ix, lane, cq1, 4); cv_issue_q(a.cv, ix, lane, cq2, 8); cv_issue_q(a.cv, ix, lane, cq3, 12); cv_finish(a.cv, ix, lane, cq0, cq1, cq2, cq3, CVS); }
.LBB0_343:
	s_lshr_b32 s8, s40, 6
	v_cvt_f32_u32_e32 v18, s8
	s_sub_i32 s78, 0, s8
	s_abs_i32 s77, s41
	s_ashr_i32 s9, s41, 31
	v_rcp_iflag_f32_e32 v18, v18
	s_nop 0
	v_mul_f32_e32 v18, 0x4f7ffffe, v18
	v_cvt_u32_f32_e32 v18, v18
	s_nop 0
	v_readfirstlane_b32 s79, v18
	s_mul_i32 s78, s78, s79
	s_mul_hi_u32 s78, s79, s78
	s_add_i32 s79, s79, s78
	s_mul_hi_u32 s78, s77, s79
	s_mul_i32 s79, s78, s8
	s_sub_i32 s77, s77, s79
	s_add_i32 s82, s78, 1
	s_sub_i32 s79, s77, s8
	s_cmp_ge_u32 s77, s8
	s_cselect_b32 s78, s82, s78
	s_cselect_b32 s77, s79, s77
	s_add_i32 s79, s78, 1
	s_cmp_ge_u32 s77, s8
	s_cselect_b32 s77, s79, s78
	s_xor_b32 s77, s77, s9
	s_sub_i32 s9, s77, s9
	s_mul_i32 s8, s9, s8
	s_lshl_b32 s9, s9, 6
	s_or_b32 s9, s9, 4
	s_sub_i32 s8, s41, s8
	s_mul_hi_i32 s79, s9, s40
	s_mul_i32 s78, s9, s40
	s_lshl_b32 s8, s8, 6
	s_lshl_b64 s[78:79], s[78:79], 2
	s_add_u32 s41, s2, s78
	s_addc_u32 s77, s3, s79
	s_ashr_i32 s9, s8, 31
	s_lshl_b64 s[2:3], s[8:9], 2
	v_mul_u32_u24_e32 v18, s40, v102
	s_add_u32 s2, s41, s2
	v_or_b32_e32 v18, v18, v125
	s_addc_u32 s3, s77, s3
	v_lshlrev_b32_e32 v82, 2, v18
	s_lshl_b32 s96, s40, 2
	v_lshl_add_u64 v[18:19], s[2:3], 0, v[82:83]
	v_lshl_add_u64 v[18:19], v[18:19], 0, s[96:97]
	v_lshl_add_u64 v[20:21], v[18:19], 0, s[96:97]
	v_lshl_add_u64 v[30:31], v[20:21], 0, s[96:97]
	global_load_dwordx4 v[22:25], v[18:19], off nt
	global_load_dwordx4 v[26:29], v[20:21], off nt
	s_nop 0
	global_load_dwordx4 v[18:21], v82, s[2:3] nt
	s_nop 0
	global_load_dwordx4 v[30:33], v[30:31], off nt
	s_movk_i32 s40, 0x1000
	s_and_b64 vcc, exec, s[36:37]
	s_movk_i32 s8, 0x1000
	s_mov_b64 s[2:3], s[68:69]
	s_mov_b32 s41, s76
	s_cbranch_vccnz .LBB0_348
	s_cmpk_gt_u32 s76, 0x687f
	s_cbranch_scc0 .LBB0_346
	s_add_i32 s41, s76, 0xffff9780
	s_mov_b64 s[2:3], s[52:53]
	s_movk_i32 s8, 0x1000
	s_cbranch_execz .LBB0_347
	s_branch .LBB0_348

; DI void cv_issue_q(const CvJob& j, int idx, int lane, f32x4 (&v)[4], int r0) {
;     const float* W; int K, N, item; bf16* WT; const float* ks; cv_decode(j, idx, W, K, N, WT, ks, item);
;     const int nblk = N / 64, kb = item / nblk, nb = item % nblk, k0 = 64 * kb, n0 = 64 * nb, q = lane >> 4, c16 = lane & 15;
;     const char* ub = (const char*)(W + (size_t)(k0 + r0) * N + n0);
;     const unsigned vo = (unsigned)((16 * q) * N + 4 * c16) * 4u;
; #pragma unroll
;     for (int i = 0; i < 4; ++i) v[i] = *(const f32x4*)(ub + (size_t)i * N * 4 + vo);
; }
; DI void rglru_scan_unit(Frame& F, const Mix0Args& a, int u) {
;     ...
;     if (cv_on) for (int sl = NCH / 4; sl * NGW + gw < CV_NIT; ++sl) { const int ix = sl * NGW + gw; cv_issue_q(a.cv, ix, lane, cq0, 0); cv_issue_q(a.cv, ix, lane, cq1, 4); cv_issue_q(a.cv, ix, lane, cq2, 8); cv_issue_q(a.cv, ix, lane, cq3, 12); cv_finish(a.cv, ix, lane, cq0, cq1, cq2, cq3, CVS); }
.LBB0_348:
	s_lshr_b32 s9, s8, 6
	s_waitcnt vmcnt(21)
	v_cvt_f32_u32_e32 v34, s9
	s_sub_i32 s79, 0, s9
	s_abs_i32 s78, s41
	s_ashr_i32 s77, s41, 31
	v_rcp_iflag_f32_e32 v34, v34
	s_nop 0
	v_mul_f32_e32 v34, 0x4f7ffffe, v34
	v_cvt_u32_f32_e32 v34, v34
	s_nop 0
	v_readfirstlane_b32 s82, v34
	s_mul_i32 s79, s79, s82
	s_mul_hi_u32 s79, s82, s79
	s_add_i32 s82, s82, s79
	s_mul_hi_u32 s79, s78, s82
	s_mul_i32 s82, s79, s9
	s_sub_i32 s78, s78, s82
	s_add_i32 s83, s79, 1
	s_sub_i32 s82, s78, s9
	s_cmp_ge_u32 s78, s9
	s_cselect_b32 s79, s83, s79
	s_cselect_b32 s78, s82, s78
	s_add_i32 s82, s79, 1
	s_cmp_ge_u32 s78, s9
	s_cselect_b32 s78, s82, s79
	s_xor_b32 s78, s78, s77
	s_sub_i32 s77, s78, s77
	s_mul_i32 s9, s77, s9
	s_lshl_b32 s77, s77, 6
	s_sub_i32 s9, s41, s9
	s_or_b32 s41, s77, 8
	s_mul_hi_i32 s83, s41, s8
	s_mul_i32 s82, s41, s8
	s_lshl_b32 s78, s9, 6
	s_lshl_b64 s[82:83], s[82:83], 2
	s_add_u32 s9, s2, s82
	s_addc_u32 s41, s3, s83
	s_ashr_i32 s79, s78, 31
	s_lshl_b64 s[2:3], s[78:79], 2
	v_mul_u32_u24_e32 v34, s8, v102
	s_add_u32 s2, s9, s2
	v_or_b32_e32 v34, v34, v125
	s_addc_u32 s3, s41, s3
	v_lshlrev_b32_e32 v82, 2, v34
	s_lshl_b32 s96, s8, 2
	v_lshl_add_u64 v[34:35], s[2:3], 0, v[82:83]
	v_lshl_add_u64 v[34:35], v[34:35], 0, s[96:97]
	v_lshl_add_u64 v[36:37], v[34:35], 0, s[96:97]
	s_waitcnt vmcnt(20)
	v_lshl_add_u64 v[46:47], v[36:37], 0, s[96:97]
	global_load_dwordx4 v[38:41], v[34:35], off nt
	global_load_dwordx4 v[42:45], v[36:37], off nt
	s_nop 0
	global_load_dwordx4 v[34:37], v82, s[2:3] nt
	s_nop 0
	global_load_dwordx4 v[46:49], v[46:47], off nt
	s_and_b64 vcc, exec, s[36:37]
	s_mov_b64 s[2:3], s[68:69]
	s_mov_b32 s41, s76
	s_cbranch_vccnz .LBB0_353
	s_cmpk_gt_u32 s76, 0x687f
	s_cbranch_scc0 .LBB0_351
	s_add_i32 s41, s76, 0xffff9780
	s_mov_b64 s[2:3], s[52:53]
	s_cbranch_execz .LBB0_352
	s_branch .LBB0_353

; DI void cv_issue_q(const CvJob& j, int idx, int lane, f32x4 (&v)[4], int r0) {
;     const float* W; int K, N, item; bf16* WT; const float* ks; cv_decode(j, idx, W, K, N, WT, ks, item);
;     const int nblk = N / 64, kb = item / nblk, nb = item % nblk, k0 = 64 * kb, n0 = 64 * nb, q = lane >> 4, c16 = lane & 15;
;     const char* ub = (const char*)(W + (size_t)(k0 + r0) * N + n0);
;     const unsigned vo = (unsigned)((16 * q) * N + 4 * c16) * 4u;
; #pragma unroll
;     for (int i = 0; i < 4; ++i) v[i] = *(const f32x4*)(ub + (size_t)i * N * 4 + vo);
; }
; DI void rglru_scan_unit(Frame& F, const Mix0Args& a, int u) {
;     ...
;     if (cv_on) for (int sl = NCH / 4; sl * NGW + gw < CV_NIT; ++sl) { const int ix = sl * NGW + gw; cv_issue_q(a.cv, ix, lane, cq0, 0); cv_issue_q(a.cv, ix, lane, cq1, 4); cv_issue_q(a.cv, ix, lane, cq2, 8); cv_issue_q(a.cv, ix, lane, cq3, 12); cv_finish(a.cv, ix, lane, cq0, cq1, cq2, cq3, CVS); }
.LBB0_353:
	s_lshr_b32 s8, s40, 6
	s_waitcnt vmcnt(16)
	v_cvt_f32_u32_e32 v50, s8
	s_sub_i32 s78, 0, s8
	s_abs_i32 s77, s41
	s_ashr_i32 s9, s41, 31
	v_rcp_iflag_f32_e32 v50, v50
	s_nop 0
	v_mul_f32_e32 v50, 0x4f7ffffe, v50
	v_cvt_u32_f32_e32 v50, v50
	s_nop 0
	v_readfirstlane_b32 s79, v50
	s_mul_i32 s78, s78, s79
	s_mul_hi_u32 s78, s79, s78
	s_add_i32 s79, s79, s78
	s_mul_hi_u32 s78, s77, s79
	s_mul_i32 s79, s78, s8
	s_sub_i32 s77, s77, s79
	s_add_i32 s82, s78, 1
	s_sub_i32 s79, s77, s8
	s_cmp_ge_u32 s77, s8
	s_cselect_b32 s78, s82, s78
	s_cselect_b32 s77, s79, s77
	s_add_i32 s79, s78, 1
	s_cmp_ge_u32 s77, s8
	s_cselect_b32 s77, s79, s78
	s_xor_b32 s77, s77, s9
	s_sub_i32 s9, s77, s9
	s_mul_i32 s8, s9, s8
	s_lshl_b32 s9, s9, 6
	s_or_b32 s9, s9, 12
	s_sub_i32 s8, s41, s8
	s_mul_hi_i32 s79, s9, s40
	s_mul_i32 s78, s9, s40
	s_lshl_b32 s8, s8, 6
	s_lshl_b64 s[78:79], s[78:79], 2
	s_add_u32 s41, s2, s78
	s_addc_u32 s77, s3, s79
	s_ashr_i32 s9, s8, 31
	s_lshl_b64 s[2:3], s[8:9], 2
	v_mul_u32_u24_e32 v50, s40, v102
	s_add_u32 s2, s41, s2
	v_or_b32_e32 v50, v50, v125
	s_addc_u32 s3, s77, s3
	v_lshlrev_b32_e32 v82, 2, v50
	s_lshl_b32 s96, s40, 2
	v_lshl_add_u64 v[50:51], s[2:3], 0, v[82:83]
	v_lshl_add_u64 v[50:51], v[50:51], 0, s[96:97]
	v_lshl_add_u64 v[52:53], v[50:51], 0, s[96:97]
	global_load_dwordx4 v[58:61], v[50:51], off nt
	global_load_dwordx4 v[62:65], v[52:53], off nt
	v_lshl_add_u64 v[50:51], v[52:53], 0, s[96:97]
	global_load_dwordx4 v[54:57], v82, s[2:3] nt
	s_nop 0
	global_load_dwordx4 v[50:53], v[50:51], off nt
	s_and_b64 vcc, exec, s[36:37]
	s_cbranch_vccnz .LBB0_358
	s_cmpk_gt_u32 s76, 0x687f
	s_mov_b64 s[2:3], -1
	s_cbranch_scc0 .LBB0_356
	s_add_i32 s77, s76, 0xffff9780
	s_mov_b64 s[2:3], 0
	s_mov_b64 s[40:41], s[50:51]
